# adds: m2 GLU 16-lane reductions via DPP instead of ds_bpermute; m2 SSM scan with batched LDS reads + plain fma
# speedup vs baseline: 1.0043x; 1.0043x over previous
.LBB0_392:
	v_lshl_or_b32 v38, v40, 4, v76
	s_waitcnt vmcnt(4)
	v_mfma_f32_16x16x32_bf16 v[164:167], v[66:69], v[30:33], 0
	v_ashrrev_i32_e32 v39, 31, v38
	v_add_u32_e32 v154, v79, v130
	v_lshlrev_b64 v[38:39], 8, v[38:39]
	v_mfma_f32_16x16x32_bf16 v[168:171], v[66:69], v[34:37], 0
	v_ashrrev_i32_e32 v155, 31, v154
	v_lshl_add_u64 v[38:39], v[88:89], 0, v[38:39]
	v_lshl_add_u64 v[154:155], v[154:155], 2, s[52:53]
	v_add_u32_e32 v149, 0x400, v136
	s_waitcnt vmcnt(3)
	v_lshlrev_b32_e32 v184, 16, v41
	s_waitcnt vmcnt(2)
	v_lshlrev_b32_e32 v183, 16, v42
	s_waitcnt vmcnt(1)
	v_lshlrev_b32_e32 v182, 16, v43
	s_waitcnt vmcnt(0)
	v_lshlrev_b32_e32 v181, 16, v44
	global_load_dwordx4 v[50:53], v[38:39], off
	global_load_dwordx4 v[46:49], v[38:39], off offset:64
	global_load_dwordx4 v[42:45], v[38:39], off offset:128
	s_nop 0
	global_load_dwordx4 v[38:41], v[38:39], off offset:192
	v_cndmask_b32_e64 v129, v3, v1, s[8:9]
	global_load_dword v145, v[154:155], off
	ds_write2_b32 v136, v164, v168 offset1:16
	ds_write2_b32 v136, v165, v169 offset0:132 offset1:148
	ds_write2_b32 v149, v166, v170 offset0:8 offset1:24
	ds_write2_b32 v149, v167, v171 offset0:140 offset1:156
	v_mfma_f32_16x16x32_bf16 v[164:167], v[66:69], v[22:25], 0
	v_cndmask_b32_e64 v155, v73, v71, s[8:9]
	v_cndmask_b32_e64 v154, v72, v70, s[8:9]
	v_mov_b32_e32 v132, v129
	v_mfma_f32_16x16x32_bf16 v[168:171], v[66:69], v[26:29], 0
	s_nop 7
	ds_write2_b32 v136, v164, v168 offset0:32 offset1:48
	ds_write2_b32 v136, v165, v169 offset0:164 offset1:180
	ds_write2_b32 v149, v166, v170 offset0:40 offset1:56
	ds_write2_b32 v149, v167, v171 offset0:172 offset1:188
	v_mfma_f32_16x16x32_bf16 v[164:167], v[66:69], v[16:19], 0
	v_cndmask_b32_e64 v128, v2, v0, s[8:9]
	v_add_u32_e32 v163, 32, v137
	v_add_u32_e32 v176, 0xf0, v137
	v_mfma_f32_16x16x32_bf16 v[168:171], v[66:69], v[12:15], 0
	s_nop 7
	ds_write2_b32 v136, v164, v168 offset0:64 offset1:80
	ds_write2_b32 v136, v165, v169 offset0:196 offset1:212
	ds_write2_b32 v149, v166, v170 offset0:72 offset1:88
	ds_write2_b32 v149, v167, v171 offset0:204 offset1:220
	v_mfma_f32_16x16x32_bf16 v[164:167], v[66:69], v[8:11], 0
	v_lshl_add_u32 v130, v130, 1, v139
	s_and_b64 vcc, exec, s[38:39]
	v_mfma_f32_16x16x32_bf16 v[66:69], v[66:69], v[4:7], 0
	s_nop 7
	ds_write2_b32 v136, v164, v66 offset0:96 offset1:112
	ds_write2_b32 v136, v165, v67 offset0:228 offset1:244
	ds_write2_b32 v149, v166, v68 offset0:104 offset1:120
	ds_write2_b32 v149, v167, v69 offset0:236 offset1:252
	s_waitcnt lgkmcnt(0)
	ds_read2st64_b32 v[212:213], v137 offset1:1
	v_add_u32_e32 v207, 16, v137
	ds_read2st64_b32 v[214:215], v207 offset0:2 offset1:3
	v_add_u32_e32 v207, 32, v137
	ds_read2st64_b32 v[216:217], v207 offset0:4 offset1:5
	v_add_u32_e32 v207, 48, v137
	ds_read2st64_b32 v[218:219], v207 offset0:6 offset1:7
	v_add_u32_e32 v207, 64, v137
	ds_read2st64_b32 v[220:221], v207 offset0:8 offset1:9
	v_add_u32_e32 v207, 80, v137
	ds_read2st64_b32 v[222:223], v207 offset0:10 offset1:11
	v_add_u32_e32 v207, 96, v137
	ds_read2st64_b32 v[224:225], v207 offset0:12 offset1:13
	v_add_u32_e32 v207, 112, v137
	ds_read2st64_b32 v[226:227], v207 offset0:14 offset1:15
	v_add_u32_e32 v207, 128, v137
	ds_read2st64_b32 v[228:229], v207 offset0:16 offset1:17
	v_add_u32_e32 v207, 144, v137
	ds_read2st64_b32 v[230:231], v207 offset0:18 offset1:19
	v_add_u32_e32 v207, 160, v137
	ds_read2st64_b32 v[232:233], v207 offset0:20 offset1:21
	v_add_u32_e32 v207, 176, v137
	ds_read2st64_b32 v[234:235], v207 offset0:22 offset1:23
	v_add_u32_e32 v207, 192, v137
	ds_read2st64_b32 v[236:237], v207 offset0:24 offset1:25
	v_add_u32_e32 v207, 208, v137
	ds_read2st64_b32 v[238:239], v207 offset0:26 offset1:27
	v_add_u32_e32 v207, 224, v137
	ds_read2st64_b32 v[240:241], v207 offset0:28 offset1:29
	v_add_u32_e32 v207, 240, v137
	ds_read2st64_b32 v[242:243], v207 offset0:30 offset1:31
	s_waitcnt lgkmcnt(15)
	v_fma_f32 v212, v128, v154, v212
	v_fma_f32 v213, v128, v155, v213
	v_fma_f32 v212, -v132, v155, v212
	v_fma_f32 v213, v132, v154, v213
	v_mov_b32_e32 v154, v212
	v_mov_b32_e32 v155, v213
	v_mov_b32_e32 v66, v128
	v_cvt_pk_bf16_f32 v156, v154, v155
	ds_write_b16 v138, v156
	ds_write_b16_d16_hi v138, v156 offset:128
	s_waitcnt lgkmcnt(15)
	v_fma_f32 v214, v128, v154, v214
	v_fma_f32 v215, v128, v155, v215
	v_fma_f32 v214, -v132, v155, v214
	v_fma_f32 v215, v132, v154, v215
	v_mov_b32_e32 v154, v214
	v_mov_b32_e32 v155, v215
	v_mov_b32_e32 v67, v128
	v_cvt_pk_bf16_f32 v156, v154, v155
	ds_write_b16 v138, v156 offset:272
	ds_write_b16_d16_hi v138, v156 offset:400
	s_waitcnt lgkmcnt(15)
	v_fma_f32 v216, v128, v154, v216
	v_fma_f32 v217, v128, v155, v217
	v_fma_f32 v216, -v132, v155, v216
	v_fma_f32 v217, v132, v154, v217
	v_mov_b32_e32 v154, v216
	v_mov_b32_e32 v155, v217
	v_add_u32_e32 v164, 48, v137
	v_cvt_pk_bf16_f32 v156, v154, v155
	ds_write_b16 v138, v156 offset:544
	ds_write_b16_d16_hi v138, v156 offset:672
	s_waitcnt lgkmcnt(15)
	v_fma_f32 v218, v128, v154, v218
	v_fma_f32 v219, v128, v155, v219
	v_fma_f32 v218, -v132, v155, v218
	v_fma_f32 v219, v132, v154, v219
	v_mov_b32_e32 v154, v218
	v_mov_b32_e32 v155, v219
	v_add_u32_e32 v165, 64, v137
	v_cvt_pk_bf16_f32 v156, v154, v155
	ds_write_b16 v138, v156 offset:816
	ds_write_b16_d16_hi v138, v156 offset:944
	s_waitcnt lgkmcnt(15)
	v_fma_f32 v220, v128, v154, v220
	v_fma_f32 v221, v128, v155, v221
	v_fma_f32 v220, -v132, v155, v220
	v_fma_f32 v221, v132, v154, v221
	v_mov_b32_e32 v154, v220
	v_mov_b32_e32 v155, v221
	v_add_u32_e32 v166, 0x50, v137
	v_cvt_pk_bf16_f32 v156, v154, v155
	ds_write_b16 v138, v156 offset:1088
	ds_write_b16_d16_hi v138, v156 offset:1216
	s_waitcnt lgkmcnt(15)
	v_fma_f32 v222, v128, v154, v222
	v_fma_f32 v223, v128, v155, v223
	v_fma_f32 v222, -v132, v155, v222
	v_fma_f32 v223, v132, v154, v223
	v_mov_b32_e32 v154, v222
	v_mov_b32_e32 v155, v223
	v_add_u32_e32 v167, 0x60, v137
	v_cvt_pk_bf16_f32 v156, v154, v155
	ds_write_b16 v138, v156 offset:1360
	ds_write_b16_d16_hi v138, v156 offset:1488
	s_waitcnt lgkmcnt(15)
	v_fma_f32 v224, v128, v154, v224
	v_fma_f32 v225, v128, v155, v225
	v_fma_f32 v224, -v132, v155, v224
	v_fma_f32 v225, v132, v154, v225
	v_mov_b32_e32 v154, v224
	v_mov_b32_e32 v155, v225
	v_add_u32_e32 v168, 0x70, v137
	v_cvt_pk_bf16_f32 v156, v154, v155
	ds_write_b16 v138, v156 offset:1632
	ds_write_b16_d16_hi v138, v156 offset:1760
	s_waitcnt lgkmcnt(15)
	v_fma_f32 v226, v128, v154, v226
	v_fma_f32 v227, v128, v155, v227
	v_fma_f32 v226, -v132, v155, v226
	v_fma_f32 v227, v132, v154, v227
	v_mov_b32_e32 v154, v226
	v_mov_b32_e32 v155, v227
	v_add_u32_e32 v169, 0x80, v137
	v_cvt_pk_bf16_f32 v156, v154, v155
	ds_write_b16 v138, v156 offset:1904
	ds_write_b16_d16_hi v138, v156 offset:2032
	s_waitcnt lgkmcnt(15)
	v_fma_f32 v228, v128, v154, v228
	v_fma_f32 v229, v128, v155, v229
	v_fma_f32 v228, -v132, v155, v228
	v_fma_f32 v229, v132, v154, v229
	v_mov_b32_e32 v154, v228
	v_mov_b32_e32 v155, v229
	v_add_u32_e32 v170, 0x90, v137
	v_cvt_pk_bf16_f32 v156, v154, v155
	ds_write_b16 v138, v156 offset:2176
	ds_write_b16_d16_hi v138, v156 offset:2304
	s_waitcnt lgkmcnt(15)
	v_fma_f32 v230, v128, v154, v230
	v_fma_f32 v231, v128, v155, v231
	v_fma_f32 v230, -v132, v155, v230
	v_fma_f32 v231, v132, v154, v231
	v_mov_b32_e32 v154, v230
	v_mov_b32_e32 v155, v231
	v_add_u32_e32 v171, 0xa0, v137
	v_cvt_pk_bf16_f32 v156, v154, v155
	ds_write_b16 v138, v156 offset:2448
	ds_write_b16_d16_hi v138, v156 offset:2576
	s_waitcnt lgkmcnt(15)
	v_fma_f32 v232, v128, v154, v232
	v_fma_f32 v233, v128, v155, v233
	v_fma_f32 v232, -v132, v155, v232
	v_fma_f32 v233, v132, v154, v233
	v_mov_b32_e32 v154, v232
	v_mov_b32_e32 v155, v233
	v_add_u32_e32 v172, 0xb0, v137
	v_cvt_pk_bf16_f32 v156, v154, v155
	ds_write_b16 v138, v156 offset:2720
	ds_write_b16_d16_hi v138, v156 offset:2848
	s_waitcnt lgkmcnt(15)
	v_fma_f32 v234, v128, v154, v234
	v_fma_f32 v235, v128, v155, v235
	v_fma_f32 v234, -v132, v155, v234
	v_fma_f32 v235, v132, v154, v235
	v_mov_b32_e32 v154, v234
	v_mov_b32_e32 v155, v235
	v_add_u32_e32 v173, 0xc0, v137
	v_cvt_pk_bf16_f32 v156, v154, v155
	ds_write_b16 v138, v156 offset:2992
	ds_write_b16_d16_hi v138, v156 offset:3120
	s_waitcnt lgkmcnt(15)
	v_fma_f32 v236, v128, v154, v236
	v_fma_f32 v237, v128, v155, v237
	v_fma_f32 v236, -v132, v155, v236
	v_fma_f32 v237, v132, v154, v237
	v_mov_b32_e32 v154, v236
	v_mov_b32_e32 v155, v237
	v_add_u32_e32 v174, 0xd0, v137
	v_cvt_pk_bf16_f32 v156, v154, v155
	ds_write_b16 v138, v156 offset:3264
	ds_write_b16_d16_hi v138, v156 offset:3392
	s_waitcnt lgkmcnt(15)
	v_fma_f32 v238, v128, v154, v238
	v_fma_f32 v239, v128, v155, v239
	v_fma_f32 v238, -v132, v155, v238
	v_fma_f32 v239, v132, v154, v239
	v_mov_b32_e32 v154, v238
	v_mov_b32_e32 v155, v239
	v_add_u32_e32 v175, 0xe0, v137
	v_cvt_pk_bf16_f32 v156, v154, v155
	ds_write_b16 v138, v156 offset:3536
	ds_write_b16_d16_hi v138, v156 offset:3664
	s_waitcnt lgkmcnt(15)
	v_fma_f32 v240, v128, v154, v240
	v_fma_f32 v241, v128, v155, v241
	v_fma_f32 v240, -v132, v155, v240
	v_fma_f32 v241, v132, v154, v241
	v_mov_b32_e32 v154, v240
	v_mov_b32_e32 v155, v241
	v_mov_b32_e32 v68, v129
	v_cvt_pk_bf16_f32 v156, v154, v155
	ds_write_b16 v138, v156 offset:3808
	ds_write_b16_d16_hi v138, v156 offset:3936
	v_mov_b32_e32 v69, v129
	s_waitcnt lgkmcnt(15)
	v_fma_f32 v242, v128, v154, v242
	v_fma_f32 v243, v128, v155, v243
	v_fma_f32 v242, -v132, v155, v242
	v_fma_f32 v243, v132, v154, v243
	v_mov_b32_e32 v128, v242
	v_mov_b32_e32 v129, v243
	s_nop 0
	v_cvt_pk_bf16_f32 v132, v128, v129
	ds_write_b16 v138, v132 offset:4080
	ds_write_b16_d16_hi v138, v132 offset:4208
	s_waitcnt lgkmcnt(0)
	ds_read_b128 v[186:189], v140
	ds_read_b128 v[208:211], v140 offset:64
	s_waitcnt vmcnt(4) lgkmcnt(1)
	v_mfma_f32_16x16x32_bf16 v[186:189], v[186:189], v[50:53], 0
	s_waitcnt vmcnt(3) lgkmcnt(0)
	v_mfma_f32_16x16x32_bf16 v[186:189], v[208:211], v[46:49], v[186:189]
	ds_read_b128 v[208:211], v140 offset:128
	s_waitcnt vmcnt(2) lgkmcnt(0)
	v_mfma_f32_16x16x32_bf16 v[186:189], v[208:211], v[42:45], v[186:189]
	ds_read_b128 v[208:211], v140 offset:192
	s_waitcnt vmcnt(1) lgkmcnt(0)
	v_mfma_f32_16x16x32_bf16 v[186:189], v[208:211], v[38:41], v[186:189]
	s_waitcnt vmcnt(0)
	s_nop 6
	v_fma_f32 v132, v145, v184, v186
	v_mul_f32_e32 v154, 0x3d372713, v132
	v_mul_f32_e32 v154, v132, v154
	v_fma_f32 v154, v132, v154, v132
	v_mul_f32_e32 v154, 0xbfcc422a, v154
	v_mul_f32_e32 v154, 0x3fb8aa3b, v154
	v_exp_f32_e32 v154, v154
	v_fmac_f32_e32 v189, v145, v181
	v_add_f32_e32 v154, 1.0, v154
	v_rcp_f32_e32 v154, v154
	s_nop 0
	v_mul_f32_e32 v132, v132, v154
	v_cvt_pk_bf16_f32 v132, v132, v20
	ds_write_b16 v130, v132
	v_fma_f32 v132, v145, v183, v187
	v_mul_f32_e32 v154, 0x3d372713, v132
	v_mul_f32_e32 v154, v132, v154
	v_fma_f32 v154, v132, v154, v132
	v_mul_f32_e32 v154, 0xbfcc422a, v154
	v_mul_f32_e32 v154, 0x3fb8aa3b, v154
	v_exp_f32_e32 v154, v154
	s_nop 0
	v_add_f32_e32 v154, 1.0, v154
	v_rcp_f32_e32 v154, v154
	s_nop 0
	v_mul_f32_e32 v132, v132, v154
	v_cvt_pk_bf16_f32 v132, v132, v20
	ds_write_b16 v130, v132 offset:528
	v_fma_f32 v132, v145, v182, v188
	v_mul_f32_e32 v154, 0x3d372713, v132
	v_mul_f32_e32 v154, v132, v154
	v_fma_f32 v154, v132, v154, v132
	v_mul_f32_e32 v154, 0xbfcc422a, v154
	v_mul_f32_e32 v154, 0x3fb8aa3b, v154
	v_exp_f32_e32 v154, v154
	s_nop 0
	v_add_f32_e32 v154, 1.0, v154
	v_rcp_f32_e32 v154, v154
	s_nop 0
	v_mul_f32_e32 v132, v132, v154
	v_cvt_pk_bf16_f32 v132, v132, v20
	ds_write_b16 v130, v132 offset:1056
	v_mul_f32_e32 v132, 0x3d372713, v189
	v_mul_f32_e32 v132, v189, v132
	v_fma_f32 v132, v189, v132, v189
	v_mul_f32_e32 v132, 0xbfcc422a, v132
	v_mul_f32_e32 v132, 0x3fb8aa3b, v132
	v_exp_f32_e32 v132, v132
	s_nop 0
	v_add_f32_e32 v132, 1.0, v132
	v_rcp_f32_e32 v132, v132
	s_nop 0
	v_mul_f32_e32 v132, v189, v132
	v_cvt_pk_bf16_f32 v132, v132, v20
	ds_write_b16 v130, v132 offset:1584
	s_waitcnt lgkmcnt(0)
	s_cbranch_vccnz .LBB0_396
	v_mfma_f32_16x16x32_bf16 v[182:185], v[62:65], v[30:33], 0
	v_mfma_f32_16x16x32_bf16 v[186:189], v[62:65], v[34:37], 0
	s_nop 7
	ds_write2_b32 v136, v182, v186 offset1:16
	ds_write2_b32 v136, v183, v187 offset0:132 offset1:148
	ds_write2_b32 v149, v184, v188 offset0:8 offset1:24
	ds_write2_b32 v149, v185, v189 offset0:140 offset1:156
	v_mfma_f32_16x16x32_bf16 v[182:185], v[62:65], v[22:25], 0
	v_mfma_f32_16x16x32_bf16 v[186:189], v[62:65], v[26:29], 0
	s_nop 7
	ds_write2_b32 v136, v182, v186 offset0:32 offset1:48
	ds_write2_b32 v136, v183, v187 offset0:164 offset1:180
	ds_write2_b32 v149, v184, v188 offset0:40 offset1:56
	ds_write2_b32 v149, v185, v189 offset0:172 offset1:188
	v_mfma_f32_16x16x32_bf16 v[182:185], v[62:65], v[16:19], 0
	v_mfma_f32_16x16x32_bf16 v[186:189], v[62:65], v[12:15], 0
	s_nop 7
	ds_write2_b32 v136, v182, v186 offset0:64 offset1:80
	ds_write2_b32 v136, v183, v187 offset0:196 offset1:212
	ds_write2_b32 v149, v184, v188 offset0:72 offset1:88
	ds_write2_b32 v149, v185, v189 offset0:204 offset1:220
	v_mfma_f32_16x16x32_bf16 v[182:185], v[62:65], v[8:11], 0
	v_mfma_f32_16x16x32_bf16 v[62:65], v[62:65], v[4:7], 0
	s_nop 7
	ds_write2_b32 v136, v182, v62 offset0:96 offset1:112
	ds_write2_b32 v136, v183, v63 offset0:228 offset1:244
	ds_write2_b32 v149, v184, v64 offset0:104 offset1:120
	ds_write2_b32 v149, v185, v65 offset0:236 offset1:252
	s_waitcnt lgkmcnt(0)
	ds_read2st64_b32 v[212:213], v137 offset1:1
	v_add_u32_e32 v207, 16, v137
	ds_read2st64_b32 v[214:215], v207 offset0:2 offset1:3
	v_add_u32_e32 v207, 32, v137
	ds_read2st64_b32 v[216:217], v207 offset0:4 offset1:5
	v_add_u32_e32 v207, 48, v137
	ds_read2st64_b32 v[218:219], v207 offset0:6 offset1:7
	v_add_u32_e32 v207, 64, v137
	ds_read2st64_b32 v[220:221], v207 offset0:8 offset1:9
	v_add_u32_e32 v207, 80, v137
	ds_read2st64_b32 v[222:223], v207 offset0:10 offset1:11
	v_add_u32_e32 v207, 96, v137
	ds_read2st64_b32 v[224:225], v207 offset0:12 offset1:13
	v_add_u32_e32 v207, 112, v137
	ds_read2st64_b32 v[226:227], v207 offset0:14 offset1:15
	v_add_u32_e32 v207, 128, v137
	ds_read2st64_b32 v[228:229], v207 offset0:16 offset1:17
	v_add_u32_e32 v207, 144, v137
	ds_read2st64_b32 v[230:231], v207 offset0:18 offset1:19
	v_add_u32_e32 v207, 160, v137
	ds_read2st64_b32 v[232:233], v207 offset0:20 offset1:21
	v_add_u32_e32 v207, 176, v137
	ds_read2st64_b32 v[234:235], v207 offset0:22 offset1:23
	v_add_u32_e32 v207, 192, v137
	ds_read2st64_b32 v[236:237], v207 offset0:24 offset1:25
	v_add_u32_e32 v207, 208, v137
	ds_read2st64_b32 v[238:239], v207 offset0:26 offset1:27
	v_add_u32_e32 v207, 224, v137
	ds_read2st64_b32 v[240:241], v207 offset0:28 offset1:29
	v_add_u32_e32 v207, 240, v137
	ds_read2st64_b32 v[242:243], v207 offset0:30 offset1:31
	s_nop 0
	s_nop 0
	s_waitcnt lgkmcnt(15)
	v_fma_f32 v212, v66, v128, v212
	v_fma_f32 v213, v66, v129, v213
	v_fma_f32 v212, -v68, v129, v212
	v_fma_f32 v213, v68, v128, v213
	v_mov_b32_e32 v62, v212
	v_mov_b32_e32 v63, v213
	s_nop 0
	v_cvt_pk_bf16_f32 v64, v62, v63
	ds_write_b16 v138, v64
	ds_write_b16_d16_hi v138, v64 offset:128
	s_nop 0
	s_nop 0
	s_waitcnt lgkmcnt(15)
	v_fma_f32 v214, v66, v62, v214
	v_fma_f32 v215, v66, v63, v215
	v_fma_f32 v214, -v68, v63, v214
	v_fma_f32 v215, v68, v62, v215
	v_mov_b32_e32 v62, v214
	v_mov_b32_e32 v63, v215
	s_nop 0
	v_cvt_pk_bf16_f32 v64, v62, v63
	ds_write_b16 v138, v64 offset:272
	ds_write_b16_d16_hi v138, v64 offset:400
	s_nop 0
	s_nop 0
	s_waitcnt lgkmcnt(15)
	v_fma_f32 v216, v66, v62, v216
	v_fma_f32 v217, v66, v63, v217
	v_fma_f32 v216, -v68, v63, v216
	v_fma_f32 v217, v68, v62, v217
	v_mov_b32_e32 v62, v216
	v_mov_b32_e32 v63, v217
	s_nop 0
	v_cvt_pk_bf16_f32 v64, v62, v63
	ds_write_b16 v138, v64 offset:544
	ds_write_b16_d16_hi v138, v64 offset:672
	s_nop 0
	s_nop 0
	s_waitcnt lgkmcnt(15)
	v_fma_f32 v218, v66, v62, v218
	v_fma_f32 v219, v66, v63, v219
	v_fma_f32 v218, -v68, v63, v218
	v_fma_f32 v219, v68, v62, v219
	v_mov_b32_e32 v62, v218
	v_mov_b32_e32 v63, v219
	s_nop 0
	v_cvt_pk_bf16_f32 v64, v62, v63
	ds_write_b16 v138, v64 offset:816
	ds_write_b16_d16_hi v138, v64 offset:944
	s_nop 0
	s_nop 0
	s_waitcnt lgkmcnt(15)
	v_fma_f32 v220, v66, v62, v220
	v_fma_f32 v221, v66, v63, v221
	v_fma_f32 v220, -v68, v63, v220
	v_fma_f32 v221, v68, v62, v221
	v_mov_b32_e32 v62, v220
	v_mov_b32_e32 v63, v221
	s_nop 0
	v_cvt_pk_bf16_f32 v64, v62, v63
	ds_write_b16 v138, v64 offset:1088
	ds_write_b16_d16_hi v138, v64 offset:1216
	s_nop 0
	s_nop 0
	s_waitcnt lgkmcnt(15)
	v_fma_f32 v222, v66, v62, v222
	v_fma_f32 v223, v66, v63, v223
	v_fma_f32 v222, -v68, v63, v222
	v_fma_f32 v223, v68, v62, v223
	v_mov_b32_e32 v62, v222
	v_mov_b32_e32 v63, v223
	s_nop 0
	v_cvt_pk_bf16_f32 v64, v62, v63
	ds_write_b16 v138, v64 offset:1360
	ds_write_b16_d16_hi v138, v64 offset:1488
	s_nop 0
	s_nop 0
	s_waitcnt lgkmcnt(15)
	v_fma_f32 v224, v66, v62, v224
	v_fma_f32 v225, v66, v63, v225
	v_fma_f32 v224, -v68, v63, v224
	v_fma_f32 v225, v68, v62, v225
	v_mov_b32_e32 v62, v224
	v_mov_b32_e32 v63, v225
	s_nop 0
	v_cvt_pk_bf16_f32 v64, v62, v63
	ds_write_b16 v138, v64 offset:1632
	ds_write_b16_d16_hi v138, v64 offset:1760
	s_nop 0
	s_nop 0
	s_waitcnt lgkmcnt(15)
	v_fma_f32 v226, v66, v62, v226
	v_fma_f32 v227, v66, v63, v227
	v_fma_f32 v226, -v68, v63, v226
	v_fma_f32 v227, v68, v62, v227
	v_mov_b32_e32 v62, v226
	v_mov_b32_e32 v63, v227
	s_nop 0
	v_cvt_pk_bf16_f32 v64, v62, v63
	ds_write_b16 v138, v64 offset:1904
	ds_write_b16_d16_hi v138, v64 offset:2032
	s_nop 0
	s_nop 0
	s_waitcnt lgkmcnt(15)
	v_fma_f32 v228, v66, v62, v228
	v_fma_f32 v229, v66, v63, v229
	v_fma_f32 v228, -v68, v63, v228
	v_fma_f32 v229, v68, v62, v229
	v_mov_b32_e32 v62, v228
	v_mov_b32_e32 v63, v229
	s_nop 0
	v_cvt_pk_bf16_f32 v64, v62, v63
	ds_write_b16 v138, v64 offset:2176
	ds_write_b16_d16_hi v138, v64 offset:2304
	s_nop 0
	s_nop 0
	s_waitcnt lgkmcnt(15)
	v_fma_f32 v230, v66, v62, v230
	v_fma_f32 v231, v66, v63, v231
	v_fma_f32 v230, -v68, v63, v230
	v_fma_f32 v231, v68, v62, v231
	v_mov_b32_e32 v62, v230
	v_mov_b32_e32 v63, v231
	s_nop 0
	v_cvt_pk_bf16_f32 v64, v62, v63
	ds_write_b16 v138, v64 offset:2448
	ds_write_b16_d16_hi v138, v64 offset:2576
	s_nop 0
	s_nop 0
	s_waitcnt lgkmcnt(15)
	v_fma_f32 v232, v66, v62, v232
	v_fma_f32 v233, v66, v63, v233
	v_fma_f32 v232, -v68, v63, v232
	v_fma_f32 v233, v68, v62, v233
	v_mov_b32_e32 v62, v232
	v_mov_b32_e32 v63, v233
	s_nop 0
	v_cvt_pk_bf16_f32 v64, v62, v63
	ds_write_b16 v138, v64 offset:2720
	ds_write_b16_d16_hi v138, v64 offset:2848
	s_nop 0
	s_nop 0
	s_waitcnt lgkmcnt(15)
	v_fma_f32 v234, v66, v62, v234
	v_fma_f32 v235, v66, v63, v235
	v_fma_f32 v234, -v68, v63, v234
	v_fma_f32 v235, v68, v62, v235
	v_mov_b32_e32 v62, v234
	v_mov_b32_e32 v63, v235
	s_nop 0
	v_cvt_pk_bf16_f32 v64, v62, v63
	ds_write_b16 v138, v64 offset:2992
	ds_write_b16_d16_hi v138, v64 offset:3120
	s_nop 0
	s_nop 0
	s_waitcnt lgkmcnt(15)
	v_fma_f32 v236, v66, v62, v236
	v_fma_f32 v237, v66, v63, v237
	v_fma_f32 v236, -v68, v63, v236
	v_fma_f32 v237, v68, v62, v237
	v_mov_b32_e32 v62, v236
	v_mov_b32_e32 v63, v237
	s_nop 0
	v_cvt_pk_bf16_f32 v64, v62, v63
	ds_write_b16 v138, v64 offset:3264
	ds_write_b16_d16_hi v138, v64 offset:3392
	s_nop 0
	s_nop 0
	s_waitcnt lgkmcnt(15)
	v_fma_f32 v238, v66, v62, v238
	v_fma_f32 v239, v66, v63, v239
	v_fma_f32 v238, -v68, v63, v238
	v_fma_f32 v239, v68, v62, v239
	v_mov_b32_e32 v62, v238
	v_mov_b32_e32 v63, v239
	s_nop 0
	v_cvt_pk_bf16_f32 v64, v62, v63
	ds_write_b16 v138, v64 offset:3536
	ds_write_b16_d16_hi v138, v64 offset:3664
	s_nop 0
	s_nop 0
	s_waitcnt lgkmcnt(15)
	v_fma_f32 v240, v66, v62, v240
	v_fma_f32 v241, v66, v63, v241
	v_fma_f32 v240, -v68, v63, v240
	v_fma_f32 v241, v68, v62, v241
	v_mov_b32_e32 v62, v240
	v_mov_b32_e32 v63, v241
	s_nop 0
	v_cvt_pk_bf16_f32 v64, v62, v63
	ds_write_b16 v138, v64 offset:3808
	ds_write_b16_d16_hi v138, v64 offset:3936
	s_nop 0
	s_nop 0
	s_waitcnt lgkmcnt(15)
	v_fma_f32 v242, v66, v62, v242
	v_fma_f32 v243, v66, v63, v243
	v_fma_f32 v242, -v68, v63, v242
	v_fma_f32 v243, v68, v62, v243
	v_mov_b32_e32 v128, v242
	v_mov_b32_e32 v129, v243
	s_nop 0
	v_cvt_pk_bf16_f32 v62, v128, v129
	ds_write_b16 v138, v62 offset:4080
	ds_write_b16_d16_hi v138, v62 offset:4208
	s_waitcnt lgkmcnt(0)
	ds_read_b128 v[62:65], v140
	ds_read_b128 v[182:185], v140 offset:64
	s_waitcnt lgkmcnt(1)
	v_mfma_f32_16x16x32_bf16 v[62:65], v[62:65], v[50:53], 0
	s_waitcnt lgkmcnt(0)
	v_mfma_f32_16x16x32_bf16 v[62:65], v[182:185], v[46:49], v[62:65]
	ds_read_b128 v[182:185], v140 offset:128
	s_waitcnt lgkmcnt(0)
	v_mfma_f32_16x16x32_bf16 v[62:65], v[182:185], v[42:45], v[62:65]
	ds_read_b128 v[182:185], v140 offset:192
	s_waitcnt lgkmcnt(0)
	v_mfma_f32_16x16x32_bf16 v[62:65], v[182:185], v[38:41], v[62:65]
	s_nop 7
	v_fma_f32 v62, v180, v145, v62
	v_mul_f32_e32 v132, 0x3d372713, v62
	v_mul_f32_e32 v132, v62, v132
	v_fma_f32 v132, v62, v132, v62
	v_mul_f32_e32 v132, 0xbfcc422a, v132
	v_mul_f32_e32 v132, 0x3fb8aa3b, v132
	v_exp_f32_e32 v132, v132
	v_fmac_f32_e32 v65, v177, v145
	v_add_f32_e32 v132, 1.0, v132
	v_rcp_f32_e32 v132, v132
	s_nop 0
	v_mul_f32_e32 v62, v62, v132
	v_cvt_pk_bf16_f32 v62, v62, v20
	ds_write_b16 v130, v62 offset:8448
	v_fma_f32 v62, v179, v145, v63
	v_mul_f32_e32 v63, 0x3d372713, v62
	v_mul_f32_e32 v63, v62, v63
	v_fma_f32 v63, v62, v63, v62
	v_mul_f32_e32 v63, 0xbfcc422a, v63
	v_mul_f32_e32 v63, 0x3fb8aa3b, v63
	v_exp_f32_e32 v63, v63
	s_nop 0
	v_add_f32_e32 v63, 1.0, v63
	v_rcp_f32_e32 v63, v63
	s_nop 0
	v_mul_f32_e32 v62, v62, v63
	v_cvt_pk_bf16_f32 v62, v62, v20
	ds_write_b16 v130, v62 offset:8976
	v_fma_f32 v62, v178, v145, v64
	v_mul_f32_e32 v63, 0x3d372713, v62
	v_mul_f32_e32 v63, v62, v63
	v_fma_f32 v63, v62, v63, v62
	v_mul_f32_e32 v63, 0xbfcc422a, v63
	v_mul_f32_e32 v63, 0x3fb8aa3b, v63
	v_exp_f32_e32 v63, v63
	s_nop 0
	v_add_f32_e32 v63, 1.0, v63
	v_rcp_f32_e32 v63, v63
	s_nop 0
	v_mul_f32_e32 v62, v62, v63
	v_cvt_pk_bf16_f32 v62, v62, v20
	ds_write_b16 v130, v62 offset:9504
	v_mul_f32_e32 v62, 0x3d372713, v65
	v_mul_f32_e32 v62, v65, v62
	v_fma_f32 v62, v65, v62, v65
	v_mul_f32_e32 v62, 0xbfcc422a, v62
	v_mul_f32_e32 v62, 0x3fb8aa3b, v62
	v_exp_f32_e32 v62, v62
	s_nop 0
	v_add_f32_e32 v62, 1.0, v62
	v_rcp_f32_e32 v62, v62
	s_nop 0
	v_mul_f32_e32 v62, v65, v62
	v_cvt_pk_bf16_f32 v62, v62, v20
	ds_write_b16 v130, v62 offset:10032
	s_waitcnt lgkmcnt(0)
	s_and_b64 vcc, exec, s[38:39]
	s_cbranch_vccz .LBB0_397

.LBB0_395:
	v_mfma_f32_16x16x32_bf16 v[30:33], v[54:57], v[30:33], 0
	v_mfma_f32_16x16x32_bf16 v[34:37], v[54:57], v[34:37], 0
	s_nop 7
	ds_write2_b32 v136, v30, v34 offset1:16
	ds_write2_b32 v136, v31, v35 offset0:132 offset1:148
	ds_write2_b32 v149, v32, v36 offset0:8 offset1:24
	v_mfma_f32_16x16x32_bf16 v[22:25], v[54:57], v[22:25], 0
	v_mfma_f32_16x16x32_bf16 v[26:29], v[54:57], v[26:29], 0
	ds_write2_b32 v149, v33, v37 offset0:140 offset1:156
	s_nop 6
	ds_write2_b32 v136, v22, v26 offset0:32 offset1:48
	ds_write2_b32 v136, v23, v27 offset0:164 offset1:180
	v_mfma_f32_16x16x32_bf16 v[16:19], v[54:57], v[16:19], 0
	v_mfma_f32_16x16x32_bf16 v[12:15], v[54:57], v[12:15], 0
	ds_write2_b32 v149, v24, v28 offset0:40 offset1:56
	ds_write2_b32 v149, v25, v29 offset0:172 offset1:188
	s_nop 5
	ds_write2_b32 v136, v16, v12 offset0:64 offset1:80
	ds_write2_b32 v136, v17, v13 offset0:196 offset1:212
	ds_write2_b32 v149, v18, v14 offset0:72 offset1:88
	ds_write2_b32 v149, v19, v15 offset0:204 offset1:220
	v_mfma_f32_16x16x32_bf16 v[8:11], v[54:57], v[8:11], 0
	v_mfma_f32_16x16x32_bf16 v[4:7], v[54:57], v[4:7], 0
	s_nop 7
	ds_write2_b32 v136, v8, v4 offset0:96 offset1:112
	ds_write2_b32 v136, v9, v5 offset0:228 offset1:244
	ds_write2_b32 v149, v10, v6 offset0:104 offset1:120
	ds_write2_b32 v149, v11, v7 offset0:236 offset1:252
	s_waitcnt lgkmcnt(0)
	ds_read2st64_b32 v[212:213], v137 offset1:1
	v_add_u32_e32 v207, 16, v137
	ds_read2st64_b32 v[214:215], v207 offset0:2 offset1:3
	v_add_u32_e32 v207, 32, v137
	ds_read2st64_b32 v[216:217], v207 offset0:4 offset1:5
	v_add_u32_e32 v207, 48, v137
	ds_read2st64_b32 v[218:219], v207 offset0:6 offset1:7
	v_add_u32_e32 v207, 64, v137
	ds_read2st64_b32 v[220:221], v207 offset0:8 offset1:9
	v_add_u32_e32 v207, 80, v137
	ds_read2st64_b32 v[222:223], v207 offset0:10 offset1:11
	v_add_u32_e32 v207, 96, v137
	ds_read2st64_b32 v[224:225], v207 offset0:12 offset1:13
	v_add_u32_e32 v207, 112, v137
	ds_read2st64_b32 v[226:227], v207 offset0:14 offset1:15
	v_add_u32_e32 v207, 128, v137
	ds_read2st64_b32 v[228:229], v207 offset0:16 offset1:17
	v_add_u32_e32 v207, 144, v137
	ds_read2st64_b32 v[230:231], v207 offset0:18 offset1:19
	v_add_u32_e32 v207, 160, v137
	ds_read2st64_b32 v[232:233], v207 offset0:20 offset1:21
	v_add_u32_e32 v207, 176, v137
	ds_read2st64_b32 v[234:235], v207 offset0:22 offset1:23
	v_add_u32_e32 v207, 192, v137
	ds_read2st64_b32 v[236:237], v207 offset0:24 offset1:25
	v_add_u32_e32 v207, 208, v137
	ds_read2st64_b32 v[238:239], v207 offset0:26 offset1:27
	v_add_u32_e32 v207, 224, v137
	ds_read2st64_b32 v[240:241], v207 offset0:28 offset1:29
	v_add_u32_e32 v207, 240, v137
	ds_read2st64_b32 v[242:243], v207 offset0:30 offset1:31
	s_nop 0
	s_nop 0
	s_waitcnt lgkmcnt(15)
	v_fma_f32 v212, v66, v128, v212
	v_fma_f32 v213, v66, v129, v213
	v_fma_f32 v212, -v68, v129, v212
	v_fma_f32 v213, v68, v128, v213
	v_mov_b32_e32 v4, v212
	v_mov_b32_e32 v5, v213
	s_nop 0
	v_cvt_pk_bf16_f32 v6, v4, v5
	ds_write_b16 v138, v6
	ds_write_b16_d16_hi v138, v6 offset:128
	s_nop 0
	s_nop 0
	s_waitcnt lgkmcnt(15)
	v_fma_f32 v214, v66, v4, v214
	v_fma_f32 v215, v66, v5, v215
	v_fma_f32 v214, -v68, v5, v214
	v_fma_f32 v215, v68, v4, v215
	v_mov_b32_e32 v4, v214
	v_mov_b32_e32 v5, v215
	s_nop 0
	v_cvt_pk_bf16_f32 v6, v4, v5
	ds_write_b16 v138, v6 offset:272
	ds_write_b16_d16_hi v138, v6 offset:400
	s_nop 0
	s_nop 0
	s_waitcnt lgkmcnt(15)
	v_fma_f32 v216, v66, v4, v216
	v_fma_f32 v217, v66, v5, v217
	v_fma_f32 v216, -v68, v5, v216
	v_fma_f32 v217, v68, v4, v217
	v_mov_b32_e32 v4, v216
	v_mov_b32_e32 v5, v217
	s_nop 0
	v_cvt_pk_bf16_f32 v6, v4, v5
	ds_write_b16 v138, v6 offset:544
	ds_write_b16_d16_hi v138, v6 offset:672
	s_nop 0
	s_nop 0
	s_waitcnt lgkmcnt(15)
	v_fma_f32 v218, v66, v4, v218
	v_fma_f32 v219, v66, v5, v219
	v_fma_f32 v218, -v68, v5, v218
	v_fma_f32 v219, v68, v4, v219
	v_mov_b32_e32 v4, v218
	v_mov_b32_e32 v5, v219
	s_nop 0
	v_cvt_pk_bf16_f32 v6, v4, v5
	ds_write_b16 v138, v6 offset:816
	ds_write_b16_d16_hi v138, v6 offset:944
	s_nop 0
	s_nop 0
	s_waitcnt lgkmcnt(15)
	v_fma_f32 v220, v66, v4, v220
	v_fma_f32 v221, v66, v5, v221
	v_fma_f32 v220, -v68, v5, v220
	v_fma_f32 v221, v68, v4, v221
	v_mov_b32_e32 v4, v220
	v_mov_b32_e32 v5, v221
	s_nop 0
	v_cvt_pk_bf16_f32 v6, v4, v5
	ds_write_b16 v138, v6 offset:1088
	ds_write_b16_d16_hi v138, v6 offset:1216
	s_nop 0
	s_nop 0
	s_waitcnt lgkmcnt(15)
	v_fma_f32 v222, v66, v4, v222
	v_fma_f32 v223, v66, v5, v223
	v_fma_f32 v222, -v68, v5, v222
	v_fma_f32 v223, v68, v4, v223
	v_mov_b32_e32 v4, v222
	v_mov_b32_e32 v5, v223
	s_nop 0
	v_cvt_pk_bf16_f32 v6, v4, v5
	ds_write_b16 v138, v6 offset:1360
	ds_write_b16_d16_hi v138, v6 offset:1488
	s_nop 0
	s_nop 0
	s_waitcnt lgkmcnt(15)
	v_fma_f32 v224, v66, v4, v224
	v_fma_f32 v225, v66, v5, v225
	v_fma_f32 v224, -v68, v5, v224
	v_fma_f32 v225, v68, v4, v225
	v_mov_b32_e32 v4, v224
	v_mov_b32_e32 v5, v225
	s_nop 0
	v_cvt_pk_bf16_f32 v6, v4, v5
	ds_write_b16 v138, v6 offset:1632
	ds_write_b16_d16_hi v138, v6 offset:1760
	s_nop 0
	s_nop 0
	s_waitcnt lgkmcnt(15)
	v_fma_f32 v226, v66, v4, v226
	v_fma_f32 v227, v66, v5, v227
	v_fma_f32 v226, -v68, v5, v226
	v_fma_f32 v227, v68, v4, v227
	v_mov_b32_e32 v4, v226
	v_mov_b32_e32 v5, v227
	s_nop 0
	v_cvt_pk_bf16_f32 v6, v4, v5
	ds_write_b16 v138, v6 offset:1904
	ds_write_b16_d16_hi v138, v6 offset:2032
	s_nop 0
	s_nop 0
	s_waitcnt lgkmcnt(15)
	v_fma_f32 v228, v66, v4, v228
	v_fma_f32 v229, v66, v5, v229
	v_fma_f32 v228, -v68, v5, v228
	v_fma_f32 v229, v68, v4, v229
	v_mov_b32_e32 v4, v228
	v_mov_b32_e32 v5, v229
	s_nop 0
	v_cvt_pk_bf16_f32 v6, v4, v5
	ds_write_b16 v138, v6 offset:2176
	ds_write_b16_d16_hi v138, v6 offset:2304
	s_nop 0
	s_nop 0
	s_waitcnt lgkmcnt(15)
	v_fma_f32 v230, v66, v4, v230
	v_fma_f32 v231, v66, v5, v231
	v_fma_f32 v230, -v68, v5, v230
	v_fma_f32 v231, v68, v4, v231
	v_mov_b32_e32 v4, v230
	v_mov_b32_e32 v5, v231
	s_nop 0
	v_cvt_pk_bf16_f32 v6, v4, v5
	ds_write_b16 v138, v6 offset:2448
	ds_write_b16_d16_hi v138, v6 offset:2576
	s_nop 0
	s_nop 0
	s_waitcnt lgkmcnt(15)
	v_fma_f32 v232, v66, v4, v232
	v_fma_f32 v233, v66, v5, v233
	v_fma_f32 v232, -v68, v5, v232
	v_fma_f32 v233, v68, v4, v233
	v_mov_b32_e32 v4, v232
	v_mov_b32_e32 v5, v233
	s_nop 0
	v_cvt_pk_bf16_f32 v6, v4, v5
	ds_write_b16 v138, v6 offset:2720
	ds_write_b16_d16_hi v138, v6 offset:2848
	s_nop 0
	s_nop 0
	s_waitcnt lgkmcnt(15)
	v_fma_f32 v234, v66, v4, v234
	v_fma_f32 v235, v66, v5, v235
	v_fma_f32 v234, -v68, v5, v234
	v_fma_f32 v235, v68, v4, v235
	v_mov_b32_e32 v4, v234
	v_mov_b32_e32 v5, v235
	s_nop 0
	v_cvt_pk_bf16_f32 v6, v4, v5
	ds_write_b16 v138, v6 offset:2992
	ds_write_b16_d16_hi v138, v6 offset:3120
	s_nop 0
	s_nop 0
	s_waitcnt lgkmcnt(15)
	v_fma_f32 v236, v66, v4, v236
	v_fma_f32 v237, v66, v5, v237
	v_fma_f32 v236, -v68, v5, v236
	v_fma_f32 v237, v68, v4, v237
	v_mov_b32_e32 v4, v236
	v_mov_b32_e32 v5, v237
	s_nop 0
	v_cvt_pk_bf16_f32 v6, v4, v5
	ds_write_b16 v138, v6 offset:3264
	ds_write_b16_d16_hi v138, v6 offset:3392
	s_nop 0
	s_nop 0
	s_waitcnt lgkmcnt(15)
	v_fma_f32 v238, v66, v4, v238
	v_fma_f32 v239, v66, v5, v239
	v_fma_f32 v238, -v68, v5, v238
	v_fma_f32 v239, v68, v4, v239
	v_mov_b32_e32 v4, v238
	v_mov_b32_e32 v5, v239
	s_nop 0
	v_cvt_pk_bf16_f32 v6, v4, v5
	ds_write_b16 v138, v6 offset:3536
	ds_write_b16_d16_hi v138, v6 offset:3664
	s_nop 0
	s_nop 0
	s_waitcnt lgkmcnt(15)
	v_fma_f32 v240, v66, v4, v240
	v_fma_f32 v241, v66, v5, v241
	v_fma_f32 v240, -v68, v5, v240
	v_fma_f32 v241, v68, v4, v241
	v_mov_b32_e32 v4, v240
	v_mov_b32_e32 v5, v241
	s_nop 0
	v_cvt_pk_bf16_f32 v6, v4, v5
	ds_write_b16 v138, v6 offset:3808
	ds_write_b16_d16_hi v138, v6 offset:3936
	s_nop 0
	s_nop 0
	s_waitcnt lgkmcnt(15)
	v_fma_f32 v242, v66, v4, v242
	v_fma_f32 v243, v66, v5, v243
	v_fma_f32 v242, -v68, v5, v242
	v_fma_f32 v243, v68, v4, v243
	v_mov_b32_e32 v128, v242
	v_mov_b32_e32 v129, v243
	s_nop 0
	v_cvt_pk_bf16_f32 v4, v128, v129
	ds_write_b16 v138, v4 offset:4080
	ds_write_b16_d16_hi v138, v4 offset:4208
	s_waitcnt lgkmcnt(0)
	ds_read_b128 v[4:7], v140
	ds_read_b128 v[8:11], v140 offset:64
	s_waitcnt lgkmcnt(1)
	v_mfma_f32_16x16x32_bf16 v[4:7], v[4:7], v[50:53], 0
	ds_read_b128 v[12:15], v140 offset:128
	s_waitcnt lgkmcnt(1)
	v_mfma_f32_16x16x32_bf16 v[4:7], v[8:11], v[46:49], v[4:7]
	ds_read_b128 v[8:11], v140 offset:192
	s_waitcnt lgkmcnt(1)
	v_mfma_f32_16x16x32_bf16 v[4:7], v[12:15], v[42:45], v[4:7]
	s_waitcnt lgkmcnt(0)
	v_mfma_f32_16x16x32_bf16 v[4:7], v[8:11], v[38:41], v[4:7]
	s_nop 7
	v_fma_f32 v4, v144, v145, v4
	v_mul_f32_e32 v8, 0x3d372713, v4
	v_mul_f32_e32 v8, v4, v8
	v_fma_f32 v5, v142, v145, v5
	v_fma_f32 v8, v4, v8, v4
	v_mul_f32_e32 v9, 0x3d372713, v5
	v_mul_f32_e32 v8, 0xbfcc422a, v8
	v_mul_f32_e32 v9, v5, v9
	v_mul_f32_e32 v8, 0x3fb8aa3b, v8
	v_fma_f32 v9, v5, v9, v5
	v_exp_f32_e32 v8, v8
	v_mul_f32_e32 v9, 0xbfcc422a, v9
	v_mul_f32_e32 v9, 0x3fb8aa3b, v9
	v_exp_f32_e32 v9, v9
	v_add_f32_e32 v8, 1.0, v8
	v_rcp_f32_e32 v8, v8
	v_fmac_f32_e32 v7, v131, v145
	v_add_f32_e32 v9, 1.0, v9
	v_rcp_f32_e32 v9, v9
	v_mul_f32_e32 v4, v4, v8
	v_cvt_pk_bf16_f32 v4, v4, v20
	ds_write_b16 v130, v4 offset:25344
	v_mul_f32_e32 v4, v5, v9
	v_fma_f32 v5, v143, v145, v6
	v_mul_f32_e32 v6, 0x3d372713, v5
	v_mul_f32_e32 v8, 0x3d372713, v7
	v_mul_f32_e32 v6, v5, v6
	v_mul_f32_e32 v8, v7, v8
	v_fma_f32 v6, v5, v6, v5
	v_fma_f32 v8, v7, v8, v7
	v_mul_f32_e32 v6, 0xbfcc422a, v6
	v_mul_f32_e32 v8, 0xbfcc422a, v8
	v_mul_f32_e32 v6, 0x3fb8aa3b, v6
	v_mul_f32_e32 v8, 0x3fb8aa3b, v8
	v_exp_f32_e32 v6, v6
	v_exp_f32_e32 v8, v8
	v_cvt_pk_bf16_f32 v4, v4, v20
	ds_write_b16 v130, v4 offset:25872
	v_add_f32_e32 v6, 1.0, v6
	v_add_f32_e32 v4, 1.0, v8
	v_rcp_f32_e32 v6, v6
	v_rcp_f32_e32 v4, v4
	v_mul_f32_e32 v5, v5, v6
	v_mul_f32_e32 v4, v7, v4
	v_cvt_pk_bf16_f32 v5, v5, v20
	ds_write_b16 v130, v5 offset:26400
	v_cvt_pk_bf16_f32 v4, v4, v20
	ds_write_b16 v130, v4 offset:26928
	s_waitcnt lgkmcnt(0)
	s_andn2_b64 vcc, exec, s[46:47]
	s_cbranch_vccnz .LBB0_359
	s_branch .LBB0_399

.LBB0_397:
	v_mfma_f32_16x16x32_bf16 v[62:65], v[58:61], v[30:33], 0
	v_mfma_f32_16x16x32_bf16 v[178:181], v[58:61], v[34:37], 0
	s_nop 7
	ds_write2_b32 v136, v62, v178 offset1:16
	ds_write2_b32 v136, v63, v179 offset0:132 offset1:148
	ds_write2_b32 v149, v64, v180 offset0:8 offset1:24
	ds_write2_b32 v149, v65, v181 offset0:140 offset1:156
	v_mfma_f32_16x16x32_bf16 v[62:65], v[58:61], v[22:25], 0
	v_mfma_f32_16x16x32_bf16 v[178:181], v[58:61], v[26:29], 0
	s_nop 7
	ds_write2_b32 v136, v62, v178 offset0:32 offset1:48
	ds_write2_b32 v136, v63, v179 offset0:164 offset1:180
	ds_write2_b32 v149, v64, v180 offset0:40 offset1:56
	ds_write2_b32 v149, v65, v181 offset0:172 offset1:188
	v_mfma_f32_16x16x32_bf16 v[62:65], v[58:61], v[16:19], 0
	v_mfma_f32_16x16x32_bf16 v[178:181], v[58:61], v[12:15], 0
	s_nop 7
	ds_write2_b32 v136, v62, v178 offset0:64 offset1:80
	ds_write2_b32 v136, v63, v179 offset0:196 offset1:212
	ds_write2_b32 v149, v64, v180 offset0:72 offset1:88
	ds_write2_b32 v149, v65, v181 offset0:204 offset1:220
	v_mfma_f32_16x16x32_bf16 v[62:65], v[58:61], v[8:11], 0
	v_mfma_f32_16x16x32_bf16 v[58:61], v[58:61], v[4:7], 0
	s_nop 7
	ds_write2_b32 v136, v62, v58 offset0:96 offset1:112
	ds_write2_b32 v136, v63, v59 offset0:228 offset1:244
	ds_write2_b32 v149, v64, v60 offset0:104 offset1:120
	ds_write2_b32 v149, v65, v61 offset0:236 offset1:252
	s_waitcnt lgkmcnt(0)
	ds_read2st64_b32 v[212:213], v137 offset1:1
	v_add_u32_e32 v207, 16, v137
	ds_read2st64_b32 v[214:215], v207 offset0:2 offset1:3
	v_add_u32_e32 v207, 32, v137
	ds_read2st64_b32 v[216:217], v207 offset0:4 offset1:5
	v_add_u32_e32 v207, 48, v137
	ds_read2st64_b32 v[218:219], v207 offset0:6 offset1:7
	v_add_u32_e32 v207, 64, v137
	ds_read2st64_b32 v[220:221], v207 offset0:8 offset1:9
	v_add_u32_e32 v207, 80, v137
	ds_read2st64_b32 v[222:223], v207 offset0:10 offset1:11
	v_add_u32_e32 v207, 96, v137
	ds_read2st64_b32 v[224:225], v207 offset0:12 offset1:13
	v_add_u32_e32 v207, 112, v137
	ds_read2st64_b32 v[226:227], v207 offset0:14 offset1:15
	v_add_u32_e32 v207, 128, v137
	ds_read2st64_b32 v[228:229], v207 offset0:16 offset1:17
	v_add_u32_e32 v207, 144, v137
	ds_read2st64_b32 v[230:231], v207 offset0:18 offset1:19
	v_add_u32_e32 v207, 160, v137
	ds_read2st64_b32 v[232:233], v207 offset0:20 offset1:21
	v_add_u32_e32 v207, 176, v137
	ds_read2st64_b32 v[234:235], v207 offset0:22 offset1:23
	v_add_u32_e32 v207, 192, v137
	ds_read2st64_b32 v[236:237], v207 offset0:24 offset1:25
	v_add_u32_e32 v207, 208, v137
	ds_read2st64_b32 v[238:239], v207 offset0:26 offset1:27
	v_add_u32_e32 v207, 224, v137
	ds_read2st64_b32 v[240:241], v207 offset0:28 offset1:29
	v_add_u32_e32 v207, 240, v137
	ds_read2st64_b32 v[242:243], v207 offset0:30 offset1:31
	s_nop 0
	s_nop 0
	s_waitcnt lgkmcnt(15)
	v_fma_f32 v212, v66, v128, v212
	v_fma_f32 v213, v66, v129, v213
	v_fma_f32 v212, -v68, v129, v212
	v_fma_f32 v213, v68, v128, v213
	v_mov_b32_e32 v58, v212
	v_mov_b32_e32 v59, v213
	s_nop 0
	v_cvt_pk_bf16_f32 v60, v58, v59
	ds_write_b16 v138, v60
	ds_write_b16_d16_hi v138, v60 offset:128
	s_nop 0
	s_nop 0
	s_waitcnt lgkmcnt(15)
	v_fma_f32 v214, v66, v58, v214
	v_fma_f32 v215, v66, v59, v215
	v_fma_f32 v214, -v68, v59, v214
	v_fma_f32 v215, v68, v58, v215
	v_mov_b32_e32 v58, v214
	v_mov_b32_e32 v59, v215
	s_nop 0
	v_cvt_pk_bf16_f32 v60, v58, v59
	ds_write_b16 v138, v60 offset:272
	ds_write_b16_d16_hi v138, v60 offset:400
	s_nop 0
	s_nop 0
	s_waitcnt lgkmcnt(15)
	v_fma_f32 v216, v66, v58, v216
	v_fma_f32 v217, v66, v59, v217
	v_fma_f32 v216, -v68, v59, v216
	v_fma_f32 v217, v68, v58, v217
	v_mov_b32_e32 v58, v216
	v_mov_b32_e32 v59, v217
	s_nop 0
	v_cvt_pk_bf16_f32 v60, v58, v59
	ds_write_b16 v138, v60 offset:544
	ds_write_b16_d16_hi v138, v60 offset:672
	s_nop 0
	s_nop 0
	s_waitcnt lgkmcnt(15)
	v_fma_f32 v218, v66, v58, v218
	v_fma_f32 v219, v66, v59, v219
	v_fma_f32 v218, -v68, v59, v218
	v_fma_f32 v219, v68, v58, v219
	v_mov_b32_e32 v58, v218
	v_mov_b32_e32 v59, v219
	s_nop 0
	v_cvt_pk_bf16_f32 v60, v58, v59
	ds_write_b16 v138, v60 offset:816
	ds_write_b16_d16_hi v138, v60 offset:944
	s_nop 0
	s_nop 0
	s_waitcnt lgkmcnt(15)
	v_fma_f32 v220, v66, v58, v220
	v_fma_f32 v221, v66, v59, v221
	v_fma_f32 v220, -v68, v59, v220
	v_fma_f32 v221, v68, v58, v221
	v_mov_b32_e32 v58, v220
	v_mov_b32_e32 v59, v221
	s_nop 0
	v_cvt_pk_bf16_f32 v60, v58, v59
	ds_write_b16 v138, v60 offset:1088
	ds_write_b16_d16_hi v138, v60 offset:1216
	s_nop 0
	s_nop 0
	s_waitcnt lgkmcnt(15)
	v_fma_f32 v222, v66, v58, v222
	v_fma_f32 v223, v66, v59, v223
	v_fma_f32 v222, -v68, v59, v222
	v_fma_f32 v223, v68, v58, v223
	v_mov_b32_e32 v58, v222
	v_mov_b32_e32 v59, v223
	s_nop 0
	v_cvt_pk_bf16_f32 v60, v58, v59
	ds_write_b16 v138, v60 offset:1360
	ds_write_b16_d16_hi v138, v60 offset:1488
	s_nop 0
	s_nop 0
	s_waitcnt lgkmcnt(15)
	v_fma_f32 v224, v66, v58, v224
	v_fma_f32 v225, v66, v59, v225
	v_fma_f32 v224, -v68, v59, v224
	v_fma_f32 v225, v68, v58, v225
	v_mov_b32_e32 v58, v224
	v_mov_b32_e32 v59, v225
	s_nop 0
	v_cvt_pk_bf16_f32 v60, v58, v59
	ds_write_b16 v138, v60 offset:1632
	ds_write_b16_d16_hi v138, v60 offset:1760
	s_nop 0
	s_nop 0
	s_waitcnt lgkmcnt(15)
	v_fma_f32 v226, v66, v58, v226
	v_fma_f32 v227, v66, v59, v227
	v_fma_f32 v226, -v68, v59, v226
	v_fma_f32 v227, v68, v58, v227
	v_mov_b32_e32 v58, v226
	v_mov_b32_e32 v59, v227
	s_nop 0
	v_cvt_pk_bf16_f32 v60, v58, v59
	ds_write_b16 v138, v60 offset:1904
	ds_write_b16_d16_hi v138, v60 offset:2032
	s_nop 0
	s_nop 0
	s_waitcnt lgkmcnt(15)
	v_fma_f32 v228, v66, v58, v228
	v_fma_f32 v229, v66, v59, v229
	v_fma_f32 v228, -v68, v59, v228
	v_fma_f32 v229, v68, v58, v229
	v_mov_b32_e32 v58, v228
	v_mov_b32_e32 v59, v229
	s_nop 0
	v_cvt_pk_bf16_f32 v60, v58, v59
	ds_write_b16 v138, v60 offset:2176
	ds_write_b16_d16_hi v138, v60 offset:2304
	s_nop 0
	s_nop 0
	s_waitcnt lgkmcnt(15)
	v_fma_f32 v230, v66, v58, v230
	v_fma_f32 v231, v66, v59, v231
	v_fma_f32 v230, -v68, v59, v230
	v_fma_f32 v231, v68, v58, v231
	v_mov_b32_e32 v58, v230
	v_mov_b32_e32 v59, v231
	s_nop 0
	v_cvt_pk_bf16_f32 v60, v58, v59
	ds_write_b16 v138, v60 offset:2448
	ds_write_b16_d16_hi v138, v60 offset:2576
	s_nop 0
	s_nop 0
	s_waitcnt lgkmcnt(15)
	v_fma_f32 v232, v66, v58, v232
	v_fma_f32 v233, v66, v59, v233
	v_fma_f32 v232, -v68, v59, v232
	v_fma_f32 v233, v68, v58, v233
	v_mov_b32_e32 v58, v232
	v_mov_b32_e32 v59, v233
	s_nop 0
	v_cvt_pk_bf16_f32 v60, v58, v59
	ds_write_b16 v138, v60 offset:2720
	ds_write_b16_d16_hi v138, v60 offset:2848
	s_nop 0
	s_nop 0
	s_waitcnt lgkmcnt(15)
	v_fma_f32 v234, v66, v58, v234
	v_fma_f32 v235, v66, v59, v235
	v_fma_f32 v234, -v68, v59, v234
	v_fma_f32 v235, v68, v58, v235
	v_mov_b32_e32 v58, v234
	v_mov_b32_e32 v59, v235
	s_nop 0
	v_cvt_pk_bf16_f32 v60, v58, v59
	ds_write_b16 v138, v60 offset:2992
	ds_write_b16_d16_hi v138, v60 offset:3120
	s_nop 0
	s_nop 0
	s_waitcnt lgkmcnt(15)
	v_fma_f32 v236, v66, v58, v236
	v_fma_f32 v237, v66, v59, v237
	v_fma_f32 v236, -v68, v59, v236
	v_fma_f32 v237, v68, v58, v237
	v_mov_b32_e32 v58, v236
	v_mov_b32_e32 v59, v237
	s_nop 0
	v_cvt_pk_bf16_f32 v60, v58, v59
	ds_write_b16 v138, v60 offset:3264
	ds_write_b16_d16_hi v138, v60 offset:3392
	s_nop 0
	s_nop 0
	s_waitcnt lgkmcnt(15)
	v_fma_f32 v238, v66, v58, v238
	v_fma_f32 v239, v66, v59, v239
	v_fma_f32 v238, -v68, v59, v238
	v_fma_f32 v239, v68, v58, v239
	v_mov_b32_e32 v58, v238
	v_mov_b32_e32 v59, v239
	s_nop 0
	v_cvt_pk_bf16_f32 v60, v58, v59
	ds_write_b16 v138, v60 offset:3536
	ds_write_b16_d16_hi v138, v60 offset:3664
	s_nop 0
	s_nop 0
	s_waitcnt lgkmcnt(15)
	v_fma_f32 v240, v66, v58, v240
	v_fma_f32 v241, v66, v59, v241
	v_fma_f32 v240, -v68, v59, v240
	v_fma_f32 v241, v68, v58, v241
	v_mov_b32_e32 v58, v240
	v_mov_b32_e32 v59, v241
	s_nop 0
	v_cvt_pk_bf16_f32 v60, v58, v59
	ds_write_b16 v138, v60 offset:3808
	ds_write_b16_d16_hi v138, v60 offset:3936
	s_nop 0
	s_nop 0
	s_waitcnt lgkmcnt(15)
	v_fma_f32 v242, v66, v58, v242
	v_fma_f32 v243, v66, v59, v243
	v_fma_f32 v242, -v68, v59, v242
	v_fma_f32 v243, v68, v58, v243
	v_mov_b32_e32 v128, v242
	v_mov_b32_e32 v129, v243
	s_nop 0
	v_cvt_pk_bf16_f32 v58, v128, v129
	ds_write_b16 v138, v58 offset:4080
	ds_write_b16_d16_hi v138, v58 offset:4208
	s_waitcnt lgkmcnt(0)
	ds_read_b128 v[58:61], v140
	ds_read_b128 v[62:65], v140 offset:64
	s_waitcnt lgkmcnt(1)
	v_mfma_f32_16x16x32_bf16 v[58:61], v[58:61], v[50:53], 0
	s_waitcnt lgkmcnt(0)
	v_mfma_f32_16x16x32_bf16 v[58:61], v[62:65], v[46:49], v[58:61]
	ds_read_b128 v[62:65], v140 offset:128
	s_waitcnt lgkmcnt(0)
	v_mfma_f32_16x16x32_bf16 v[58:61], v[62:65], v[42:45], v[58:61]
	ds_read_b128 v[62:65], v140 offset:192
	s_waitcnt lgkmcnt(0)
	v_mfma_f32_16x16x32_bf16 v[58:61], v[62:65], v[38:41], v[58:61]
	s_nop 7
	v_fma_f32 v58, v162, v145, v58
	v_mul_f32_e32 v62, 0x3d372713, v58
	v_mul_f32_e32 v62, v58, v62
	v_fma_f32 v62, v58, v62, v58
	v_mul_f32_e32 v62, 0xbfcc422a, v62
	v_mul_f32_e32 v62, 0x3fb8aa3b, v62
	v_exp_f32_e32 v62, v62
	v_fmac_f32_e32 v61, v146, v145
	v_add_f32_e32 v62, 1.0, v62
	v_rcp_f32_e32 v62, v62
	s_nop 0
	v_mul_f32_e32 v58, v58, v62
	v_cvt_pk_bf16_f32 v58, v58, v20
	ds_write_b16 v130, v58 offset:16896
	v_fma_f32 v58, v148, v145, v59
	v_mul_f32_e32 v59, 0x3d372713, v58
	v_mul_f32_e32 v59, v58, v59
	v_fma_f32 v59, v58, v59, v58
	v_mul_f32_e32 v59, 0xbfcc422a, v59
	v_mul_f32_e32 v59, 0x3fb8aa3b, v59
	v_exp_f32_e32 v59, v59
	s_nop 0
	v_add_f32_e32 v59, 1.0, v59
	v_rcp_f32_e32 v59, v59
	s_nop 0
	v_mul_f32_e32 v58, v58, v59
	v_cvt_pk_bf16_f32 v58, v58, v20
	ds_write_b16 v130, v58 offset:17424
	v_fma_f32 v58, v147, v145, v60
	v_mul_f32_e32 v59, 0x3d372713, v58
	v_mul_f32_e32 v59, v58, v59
	v_fma_f32 v59, v58, v59, v58
	v_mul_f32_e32 v59, 0xbfcc422a, v59
	v_mul_f32_e32 v59, 0x3fb8aa3b, v59
	v_exp_f32_e32 v59, v59
	s_nop 0
	v_add_f32_e32 v59, 1.0, v59
	v_rcp_f32_e32 v59, v59
	s_nop 0
	v_mul_f32_e32 v58, v58, v59
	v_cvt_pk_bf16_f32 v58, v58, v20
	ds_write_b16 v130, v58 offset:17952
	v_mul_f32_e32 v58, 0x3d372713, v61
	v_mul_f32_e32 v58, v61, v58
	v_fma_f32 v58, v61, v58, v61
	v_mul_f32_e32 v58, 0xbfcc422a, v58
	v_mul_f32_e32 v58, 0x3fb8aa3b, v58
	v_exp_f32_e32 v58, v58
	s_nop 0
	v_add_f32_e32 v58, 1.0, v58
	v_rcp_f32_e32 v58, v58
	s_nop 0
	v_mul_f32_e32 v58, v61, v58
	v_cvt_pk_bf16_f32 v58, v58, v20
	ds_write_b16 v130, v58 offset:18480
	s_waitcnt lgkmcnt(0)
	s_and_b64 vcc, exec, s[38:39]
	s_cbranch_vccz .LBB0_395

.LBB0_400:
	s_mov_b32 s4, s86
	v_writelane_b32 v255, s4, 27
	v_lshlrev_b32_e32 v82, 5, v77
	v_or_b32_e32 v4, v82, v76
	v_writelane_b32 v255, s5, 28
	s_lshl_b64 s[4:5], s[86:87], 17
	s_add_u32 s4, s72, s4
	s_addc_u32 s5, s73, s5
	s_add_u32 s86, s4, 0xf1b0000
	s_addc_u32 s87, s5, 0
	v_lshlrev_b32_e32 v0, 1, v80
	v_mov_b32_e32 v1, v20
	v_ashrrev_i32_e32 v5, 31, v4
	v_lshl_add_u64 v[6:7], s[86:87], 0, v[0:1]
	v_lshlrev_b64 v[0:1], 9, v[4:5]
	v_lshl_add_u64 v[88:89], v[6:7], 0, v[0:1]
	s_waitcnt lgkmcnt(0)
	s_barrier
	global_load_dwordx4 v[0:3], v[88:89], off
	v_or_b32_e32 v4, 16, v4
	v_ashrrev_i32_e32 v5, 31, v4
	v_lshlrev_b64 v[4:5], 9, v[4:5]
	v_and_b32_e32 v8, 48, v21
	v_readlane_b32 s4, v255, 5
	v_lshl_add_u64 v[92:93], v[6:7], 0, v[4:5]
	s_movk_i32 s5, 0x210
	v_add_u32_e32 v80, s4, v8
	global_load_dwordx4 v[4:7], v[92:93], off
	v_mad_u32_u24 v77, v76, s5, v80
	ds_read_b128 v[22:25], v77
	global_load_dwordx4 v[8:11], v[88:89], off offset:64
	global_load_dwordx4 v[12:15], v[92:93], off offset:64
	ds_read_b128 v[30:33], v77 offset:64
	ds_read_b128 v[38:41], v77 offset:128
	global_load_dwordx4 v[16:19], v[88:89], off offset:128
	ds_read_b128 v[50:53], v77 offset:192
	ds_read_b128 v[58:61], v77 offset:256
	ds_read_b128 v[62:65], v77 offset:320
	ds_read_b128 v[66:69], v77 offset:384
	v_and_b32_e32 v81, 0xffffffc0, v21
	v_add_u32_e32 v83, s4, v81
	v_xor_b32_e32 v21, 1, v190
	v_lshl_add_u32 v81, v81, 2, s66
	v_cmp_eq_u32_e64 s[40:41], 0, v76
	v_lshl_add_u32 v110, v135, 2, v81
	s_waitcnt vmcnt(4) lgkmcnt(6)
	v_mfma_f32_16x16x32_bf16 v[26:29], v[22:25], v[0:3], 0
	s_waitcnt vmcnt(3)
	v_mfma_f32_16x16x32_bf16 v[34:37], v[22:25], v[4:7], 0
	global_load_dwordx4 v[22:25], v[92:93], off offset:128
	s_waitcnt vmcnt(3) lgkmcnt(5)
	v_mfma_f32_16x16x32_bf16 v[42:45], v[30:33], v[8:11], v[26:29]
	s_nop 2
	global_load_dwordx4 v[26:29], v[88:89], off offset:192
	s_waitcnt vmcnt(3)
	v_mfma_f32_16x16x32_bf16 v[46:49], v[30:33], v[12:15], v[34:37]
	global_load_dwordx4 v[30:33], v[92:93], off offset:192
	s_waitcnt vmcnt(3) lgkmcnt(4)
	v_mfma_f32_16x16x32_bf16 v[42:45], v[38:41], v[16:19], v[42:45]
	global_load_dwordx4 v[34:37], v[88:89], off offset:256
	s_waitcnt vmcnt(3)
	v_mfma_f32_16x16x32_bf16 v[46:49], v[38:41], v[22:25], v[46:49]
	global_load_dwordx4 v[38:41], v[92:93], off offset:256
	s_waitcnt vmcnt(3) lgkmcnt(3)
	v_mfma_f32_16x16x32_bf16 v[54:57], v[50:53], v[26:29], v[42:45]
	s_nop 2
	global_load_dwordx4 v[42:45], v[88:89], off offset:320
	s_waitcnt vmcnt(3)
	v_mfma_f32_16x16x32_bf16 v[50:53], v[50:53], v[30:33], v[46:49]
	s_nop 2
	global_load_dwordx4 v[46:49], v[92:93], off offset:320
	s_waitcnt vmcnt(3) lgkmcnt(2)
	v_mfma_f32_16x16x32_bf16 v[54:57], v[58:61], v[34:37], v[54:57]
	s_waitcnt vmcnt(2)
	v_mfma_f32_16x16x32_bf16 v[58:61], v[58:61], v[38:41], v[50:53]
	s_nop 2
	global_load_dwordx4 v[50:53], v[88:89], off offset:384
	s_waitcnt vmcnt(2) lgkmcnt(1)
	v_mfma_f32_16x16x32_bf16 v[70:73], v[62:65], v[42:45], v[54:57]
	s_nop 2
	global_load_dwordx4 v[54:57], v[92:93], off offset:384
	s_waitcnt vmcnt(2)
	v_mfma_f32_16x16x32_bf16 v[84:87], v[62:65], v[46:49], v[58:61]
	s_nop 2
	global_load_dwordx4 v[58:61], v[88:89], off offset:448
	global_load_dwordx4 v[62:65], v[92:93], off offset:448
	ds_read_b128 v[88:91], v77 offset:448
	v_add3_u32 v77, v83, v134, v78
	s_waitcnt vmcnt(3) lgkmcnt(1)
	v_mfma_f32_16x16x32_bf16 v[70:73], v[66:69], v[50:53], v[70:73]
	s_waitcnt vmcnt(2)
	v_mfma_f32_16x16x32_bf16 v[84:87], v[66:69], v[54:57], v[84:87]
	v_and_b32_e32 v66, 64, v190
	v_add_u32_e32 v79, 64, v66
	v_cmp_lt_i32_e32 vcc, v21, v79
	s_waitcnt vmcnt(1) lgkmcnt(0)
	v_mfma_f32_16x16x32_bf16 v[66:69], v[88:91], v[58:61], v[70:73]
	v_cndmask_b32_e32 v21, v190, v21, vcc
	v_lshlrev_b32_e32 v21, 2, v21
	s_nop 5
	v_mul_f32_e32 v66, 0xbfb8aa3b, v66
	s_waitcnt vmcnt(0)
	v_mfma_f32_16x16x32_bf16 v[70:73], v[88:91], v[62:65], v[84:87]
	v_exp_f32_e32 v66, v66
	s_nop 1
	ds_read_u16 v84, v77
	ds_read_u16 v77, v77 offset:32
	s_nop 2
	v_mul_f32_e32 v70, 0xbfb8aa3b, v70
	v_exp_f32_e32 v70, v70
	v_add_f32_e32 v66, 1.0, v66
	v_rcp_f32_e32 v66, v66
	s_waitcnt lgkmcnt(0)
	v_lshlrev_b32_e32 v77, 16, v77
	v_add_f32_e32 v70, 1.0, v70
	v_rcp_f32_e32 v70, v70
	v_lshlrev_b32_e32 v84, 16, v84
	v_mul_f32_e32 v109, v66, v84
	v_xor_b32_e32 v84, 4, v190
	v_mul_f32_e32 v108, v70, v77
	v_mul_f32_e32 v66, v108, v108
	v_fmac_f32_e32 v66, v109, v109
	s_nop 1
	v_mov_b32_dpp v70, v66 quad_perm:[1,0,3,2] row_mask:0xf bank_mask:0xf
	v_xor_b32_e32 v77, 2, v190
	v_cmp_lt_i32_e32 vcc, v77, v79
	s_waitcnt lgkmcnt(0)
	v_add_f32_e32 v66, v66, v70
	v_cndmask_b32_e32 v77, v190, v77, vcc
	v_lshlrev_b32_e32 v77, 2, v77
	s_nop 1
	v_mov_b32_dpp v70, v66 quad_perm:[2,3,0,1] row_mask:0xf bank_mask:0xf
	v_cmp_lt_i32_e32 vcc, v84, v79
	s_waitcnt lgkmcnt(0)
	v_add_f32_e32 v66, v66, v70
	v_cndmask_b32_e32 v84, v190, v84, vcc
	v_lshlrev_b32_e32 v133, 2, v84
	s_nop 1
	v_mov_b32_dpp v70, v66 row_half_mirror row_mask:0xf bank_mask:0xf
	v_xor_b32_e32 v84, 8, v190
	v_cmp_lt_i32_e32 vcc, v84, v79
	s_waitcnt lgkmcnt(0)
	v_add_f32_e32 v66, v66, v70
	v_cndmask_b32_e32 v84, v190, v84, vcc
	v_lshlrev_b32_e32 v134, 2, v84
	s_nop 1
	v_mov_b32_dpp v70, v66 row_mirror row_mask:0xf bank_mask:0xf
	s_and_saveexec_b64 s[4:5], s[40:41]
	s_cbranch_execz .LBB0_402
	s_waitcnt lgkmcnt(0)
	v_add_f32_e32 v66, v66, v70
	ds_write_b32 v110, v66
.LBB0_402:
	s_or_b64 exec, exec, s[4:5]
	v_mul_f32_e32 v71, 0xbfb8aa3b, v71
	v_or_b32_e32 v105, 1, v135
	v_mul_f32_e32 v67, 0xbfb8aa3b, v67
	v_exp_f32_e32 v71, v71
	v_mul_u32_u24_e32 v66, 0x210, v105
	v_exp_f32_e32 v67, v67
	s_waitcnt lgkmcnt(0)
	v_add3_u32 v70, v83, v66, v78
	ds_read_u16 v81, v70
	ds_read_u16 v70, v70 offset:32
	v_add_f32_e32 v71, 1.0, v71
	v_add_f32_e32 v67, 1.0, v67
	v_rcp_f32_e32 v71, v71
	v_rcp_f32_e32 v67, v67
	s_waitcnt lgkmcnt(0)
	v_lshlrev_b32_e32 v70, 16, v70
	v_lshlrev_b32_e32 v81, 16, v81
	v_mul_f32_e32 v106, v71, v70
	v_mul_f32_e32 v107, v67, v81
	v_mul_f32_e32 v67, v106, v106
	v_fmac_f32_e32 v67, v107, v107
	s_nop 1
	v_mov_b32_dpp v70, v67 quad_perm:[1,0,3,2] row_mask:0xf bank_mask:0xf
	s_waitcnt lgkmcnt(0)
	v_add_f32_e32 v67, v67, v70
	s_nop 1
	v_mov_b32_dpp v70, v67 quad_perm:[2,3,0,1] row_mask:0xf bank_mask:0xf
	s_waitcnt lgkmcnt(0)
	v_add_f32_e32 v67, v67, v70
	s_nop 1
	v_mov_b32_dpp v70, v67 row_half_mirror row_mask:0xf bank_mask:0xf
	s_waitcnt lgkmcnt(0)
	v_add_f32_e32 v67, v67, v70
	s_nop 1
	v_mov_b32_dpp v70, v67 row_mirror row_mask:0xf bank_mask:0xf
	s_and_saveexec_b64 s[4:5], s[40:41]
	s_cbranch_execz .LBB0_404
	s_waitcnt lgkmcnt(0)
	v_add_f32_e32 v67, v67, v70
	ds_write_b32 v110, v67 offset:4
.LBB0_404:
	s_or_b64 exec, exec, s[4:5]
	v_mul_f32_e32 v67, 0xbfb8aa3b, v68
	v_mul_f32_e32 v68, 0xbfb8aa3b, v72
	v_exp_f32_e32 v68, v68
	v_add_u32_e32 v66, 0x210, v66
	v_exp_f32_e32 v67, v67
	v_add3_u32 v66, v83, v66, v78
	s_waitcnt lgkmcnt(0)
	ds_read_u16 v70, v66
	ds_read_u16 v71, v66 offset:32
	v_add_f32_e32 v68, 1.0, v68
	v_add_f32_e32 v67, 1.0, v67
	v_rcp_f32_e32 v68, v68
	v_rcp_f32_e32 v67, v67
	s_waitcnt lgkmcnt(0)
	v_lshlrev_b32_e32 v71, 16, v71
	v_lshlrev_b32_e32 v70, 16, v70
	v_mul_f32_e32 v103, v68, v71
	v_mul_f32_e32 v104, v67, v70
	v_mul_f32_e32 v67, v103, v103
	v_fmac_f32_e32 v67, v104, v104
	s_nop 1
	v_mov_b32_dpp v68, v67 quad_perm:[1,0,3,2] row_mask:0xf bank_mask:0xf
	s_waitcnt lgkmcnt(0)
	v_add_f32_e32 v67, v67, v68
	s_nop 1
	v_mov_b32_dpp v68, v67 quad_perm:[2,3,0,1] row_mask:0xf bank_mask:0xf
	s_waitcnt lgkmcnt(0)
	v_add_f32_e32 v67, v67, v68
	s_nop 1
	v_mov_b32_dpp v68, v67 row_half_mirror row_mask:0xf bank_mask:0xf
	s_waitcnt lgkmcnt(0)
	v_add_f32_e32 v67, v67, v68
	s_nop 1
	v_mov_b32_dpp v68, v67 row_mirror row_mask:0xf bank_mask:0xf
	s_and_saveexec_b64 s[4:5], s[40:41]
	s_cbranch_execz .LBB0_406
	s_waitcnt lgkmcnt(0)
	v_add_f32_e32 v67, v67, v68
	ds_write_b32 v110, v67 offset:8
.LBB0_406:
	s_or_b64 exec, exec, s[4:5]
	s_waitcnt lgkmcnt(0)
	v_mul_f32_e32 v68, 0xbfb8aa3b, v73
	v_mul_f32_e32 v67, 0xbfb8aa3b, v69
	v_exp_f32_e32 v68, v68
	v_exp_f32_e32 v67, v67
	ds_read_u16 v69, v66 offset:528
	ds_read_u16 v66, v66 offset:560
	v_add_f32_e32 v68, 1.0, v68
	v_add_f32_e32 v67, 1.0, v67
	v_rcp_f32_e32 v68, v68
	v_rcp_f32_e32 v67, v67
	s_waitcnt lgkmcnt(0)
	v_lshlrev_b32_e32 v66, 16, v66
	v_lshlrev_b32_e32 v69, 16, v69
	v_mul_f32_e32 v100, v68, v66
	v_mul_f32_e32 v101, v67, v69
	v_mul_f32_e32 v66, v100, v100
	v_fmac_f32_e32 v66, v101, v101
	s_nop 1
	v_mov_b32_dpp v67, v66 quad_perm:[1,0,3,2] row_mask:0xf bank_mask:0xf
	s_waitcnt lgkmcnt(0)
	v_add_f32_e32 v66, v66, v67
	s_nop 1
	v_mov_b32_dpp v67, v66 quad_perm:[2,3,0,1] row_mask:0xf bank_mask:0xf
	s_waitcnt lgkmcnt(0)
	v_add_f32_e32 v66, v66, v67
	s_nop 1
	v_mov_b32_dpp v67, v66 row_half_mirror row_mask:0xf bank_mask:0xf
	s_waitcnt lgkmcnt(0)
	v_add_f32_e32 v66, v66, v67
	s_nop 1
	v_mov_b32_dpp v67, v66 row_mirror row_mask:0xf bank_mask:0xf
	s_and_saveexec_b64 s[4:5], s[40:41]
	s_cbranch_execz .LBB0_408
	s_waitcnt lgkmcnt(0)
	v_add_f32_e32 v66, v66, v67
	ds_write_b32 v110, v66 offset:12
.LBB0_408:
	s_or_b64 exec, exec, s[4:5]
	v_mul_u32_u24_e32 v66, 0x210, v76
	s_and_b64 vcc, exec, s[38:39]
	v_add_u32_e32 v94, v80, v66
	v_or_b32_e32 v98, 16, v135
	s_cbranch_vccnz .LBB0_418
	s_waitcnt lgkmcnt(0)
	ds_read_b128 v[66:69], v94 offset:8448
	ds_read_b128 v[84:87], v94 offset:8512
	v_mul_u32_u24_e32 v80, 0x210, v98
	v_add3_u32 v81, v83, v80, v78
	s_waitcnt lgkmcnt(1)
	v_mfma_f32_16x16x32_bf16 v[70:73], v[66:69], v[0:3], 0
	v_mfma_f32_16x16x32_bf16 v[66:69], v[66:69], v[4:7], 0
	s_waitcnt lgkmcnt(0)
	v_mfma_f32_16x16x32_bf16 v[70:73], v[84:87], v[8:11], v[70:73]
	v_mfma_f32_16x16x32_bf16 v[66:69], v[84:87], v[12:15], v[66:69]
	ds_read_b128 v[84:87], v94 offset:8576
	s_waitcnt lgkmcnt(0)
	v_mfma_f32_16x16x32_bf16 v[70:73], v[84:87], v[16:19], v[70:73]
	v_mfma_f32_16x16x32_bf16 v[66:69], v[84:87], v[22:25], v[66:69]
	ds_read_b128 v[84:87], v94 offset:8640
	s_waitcnt lgkmcnt(0)
	v_mfma_f32_16x16x32_bf16 v[70:73], v[84:87], v[26:29], v[70:73]
	v_mfma_f32_16x16x32_bf16 v[66:69], v[84:87], v[30:33], v[66:69]
	ds_read_b128 v[84:87], v94 offset:8704
	s_waitcnt lgkmcnt(0)
	v_mfma_f32_16x16x32_bf16 v[70:73], v[84:87], v[34:37], v[70:73]
	v_mfma_f32_16x16x32_bf16 v[66:69], v[84:87], v[38:41], v[66:69]
	ds_read_b128 v[84:87], v94 offset:8768
	s_waitcnt lgkmcnt(0)
	v_mfma_f32_16x16x32_bf16 v[70:73], v[84:87], v[42:45], v[70:73]
	v_mfma_f32_16x16x32_bf16 v[66:69], v[84:87], v[46:49], v[66:69]
	ds_read_b128 v[84:87], v94 offset:8832
	s_waitcnt lgkmcnt(0)
	v_mfma_f32_16x16x32_bf16 v[70:73], v[84:87], v[50:53], v[70:73]
	v_mfma_f32_16x16x32_bf16 v[66:69], v[84:87], v[54:57], v[66:69]
	ds_read_b128 v[84:87], v94 offset:8896
	s_waitcnt lgkmcnt(0)
	v_mfma_f32_16x16x32_bf16 v[70:73], v[84:87], v[58:61], v[70:73]
	s_nop 7
	v_mul_f32_e32 v70, 0xbfb8aa3b, v70
	v_mfma_f32_16x16x32_bf16 v[66:69], v[84:87], v[62:65], v[66:69]
	v_exp_f32_e32 v70, v70
	s_nop 0
	v_add_f32_e32 v70, 1.0, v70
	v_rcp_f32_e32 v85, v70
	s_nop 3
	v_mul_f32_e32 v66, 0xbfb8aa3b, v66
	v_exp_f32_e32 v66, v66
	s_nop 0
	v_add_f32_e32 v66, 1.0, v66
	v_rcp_f32_e32 v84, v66
	ds_read_u16 v66, v81
	ds_read_u16 v70, v81 offset:32
	s_waitcnt lgkmcnt(1)
	v_lshlrev_b32_e32 v87, 16, v66
	s_waitcnt lgkmcnt(0)
	v_lshlrev_b32_e32 v86, 16, v70
	v_pk_mul_f32 v[88:89], v[84:85], v[86:87]
	s_nop 0
	v_pk_mul_f32 v[84:85], v[88:89], v[88:89]
	s_nop 0
	v_add_f32_e32 v66, v85, v84
	s_nop 1
	v_mov_b32_dpp v70, v66 quad_perm:[1,0,3,2] row_mask:0xf bank_mask:0xf
	s_waitcnt lgkmcnt(0)
	v_add_f32_e32 v66, v66, v70
	s_nop 1
	v_mov_b32_dpp v70, v66 quad_perm:[2,3,0,1] row_mask:0xf bank_mask:0xf
	s_waitcnt lgkmcnt(0)
	v_add_f32_e32 v66, v66, v70
	s_nop 1
	v_mov_b32_dpp v70, v66 row_half_mirror row_mask:0xf bank_mask:0xf
	s_waitcnt lgkmcnt(0)
	v_add_f32_e32 v66, v66, v70
	s_nop 1
	v_mov_b32_dpp v70, v66 row_mirror row_mask:0xf bank_mask:0xf
	s_and_saveexec_b64 s[4:5], s[40:41]
	s_cbranch_execz .LBB0_411
	s_waitcnt lgkmcnt(0)
	v_add_f32_e32 v66, v66, v70
	ds_write_b32 v110, v66 offset:64
.LBB0_411:
	s_or_b64 exec, exec, s[4:5]
	v_mul_f32_e32 v66, 0xbfb8aa3b, v71
	v_mul_f32_e32 v67, 0xbfb8aa3b, v67
	s_waitcnt lgkmcnt(0)
	v_exp_f32_e32 v70, v66
	v_exp_f32_e32 v67, v67
	v_add_u32_e32 v66, 0x210, v80
	v_add3_u32 v80, v83, v66, v78
	ds_read_u16 v81, v80
	ds_read_u16 v80, v80 offset:32
	v_add_f32_e32 v70, 1.0, v70
	v_add_f32_e32 v67, 1.0, v67
	v_rcp_f32_e32 v71, v70
	v_rcp_f32_e32 v70, v67
	s_waitcnt lgkmcnt(1)
	v_lshlrev_b32_e32 v81, 16, v81
	s_waitcnt lgkmcnt(0)
	v_lshlrev_b32_e32 v80, 16, v80
	v_pk_mul_f32 v[86:87], v[70:71], v[80:81]
	s_nop 0
	v_pk_mul_f32 v[70:71], v[86:87], v[86:87]
	s_nop 0
	v_add_f32_e32 v67, v71, v70
	s_nop 1
	v_mov_b32_dpp v70, v67 quad_perm:[1,0,3,2] row_mask:0xf bank_mask:0xf
	s_waitcnt lgkmcnt(0)
	v_add_f32_e32 v67, v67, v70
	s_nop 1
	v_mov_b32_dpp v70, v67 quad_perm:[2,3,0,1] row_mask:0xf bank_mask:0xf
	s_waitcnt lgkmcnt(0)
	v_add_f32_e32 v67, v67, v70
	s_nop 1
	v_mov_b32_dpp v70, v67 row_half_mirror row_mask:0xf bank_mask:0xf
	s_waitcnt lgkmcnt(0)
	v_add_f32_e32 v67, v67, v70
	s_nop 1
	v_mov_b32_dpp v70, v67 row_mirror row_mask:0xf bank_mask:0xf
	s_and_saveexec_b64 s[4:5], s[40:41]
	s_cbranch_execz .LBB0_413
	s_waitcnt lgkmcnt(0)
	v_add_f32_e32 v67, v67, v70
	ds_write_b32 v110, v67 offset:68
.LBB0_413:
	s_or_b64 exec, exec, s[4:5]
	v_mul_f32_e32 v67, 0xbfb8aa3b, v72
	v_exp_f32_e32 v67, v67
	v_mul_f32_e32 v68, 0xbfb8aa3b, v68
	v_exp_f32_e32 v68, v68
	v_add_u32_e32 v66, 0x210, v66
	v_add3_u32 v66, v83, v66, v78
	v_add_f32_e32 v67, 1.0, v67
	v_rcp_f32_e32 v71, v67
	ds_read_u16 v67, v66
	ds_read_u16 v72, v66 offset:32
	v_add_f32_e32 v68, 1.0, v68
	s_waitcnt lgkmcnt(2)
	v_rcp_f32_e32 v70, v68
	s_waitcnt lgkmcnt(1)
	v_lshlrev_b32_e32 v81, 16, v67
	s_waitcnt lgkmcnt(0)
	v_lshlrev_b32_e32 v80, 16, v72
	v_pk_mul_f32 v[84:85], v[70:71], v[80:81]
	s_nop 0
	v_pk_mul_f32 v[70:71], v[84:85], v[84:85]
	s_nop 0
	v_add_f32_e32 v67, v71, v70
	s_nop 1
	v_mov_b32_dpp v68, v67 quad_perm:[1,0,3,2] row_mask:0xf bank_mask:0xf
	s_waitcnt lgkmcnt(0)
	v_add_f32_e32 v67, v67, v68
	s_nop 1
	v_mov_b32_dpp v68, v67 quad_perm:[2,3,0,1] row_mask:0xf bank_mask:0xf
	s_waitcnt lgkmcnt(0)
	v_add_f32_e32 v67, v67, v68
	s_nop 1
	v_mov_b32_dpp v68, v67 row_half_mirror row_mask:0xf bank_mask:0xf
	s_waitcnt lgkmcnt(0)
	v_add_f32_e32 v67, v67, v68
	s_nop 1
	v_mov_b32_dpp v68, v67 row_mirror row_mask:0xf bank_mask:0xf
	s_and_saveexec_b64 s[4:5], s[40:41]
	s_cbranch_execz .LBB0_415
	s_waitcnt lgkmcnt(0)
	v_add_f32_e32 v67, v67, v68
	ds_write_b32 v110, v67 offset:72
.LBB0_415:
	s_or_b64 exec, exec, s[4:5]
	v_mul_f32_e32 v67, 0xbfb8aa3b, v73
	s_waitcnt lgkmcnt(0)
	v_mul_f32_e32 v68, 0xbfb8aa3b, v69
	v_exp_f32_e32 v67, v67
	v_exp_f32_e32 v68, v68
	ds_read_u16 v69, v66 offset:528
	ds_read_u16 v70, v66 offset:560
	v_add_f32_e32 v67, 1.0, v67
	v_add_f32_e32 v66, 1.0, v68
	v_rcp_f32_e32 v67, v67
	v_rcp_f32_e32 v66, v66
	s_waitcnt lgkmcnt(1)
	v_lshlrev_b32_e32 v69, 16, v69
	s_waitcnt lgkmcnt(0)
	v_lshlrev_b32_e32 v68, 16, v70
	v_pk_mul_f32 v[80:81], v[66:67], v[68:69]
	s_nop 0
	v_pk_mul_f32 v[66:67], v[80:81], v[80:81]
	s_nop 0
	v_add_f32_e32 v66, v67, v66
	s_nop 1
	v_mov_b32_dpp v67, v66 quad_perm:[1,0,3,2] row_mask:0xf bank_mask:0xf
	s_waitcnt lgkmcnt(0)
	v_add_f32_e32 v66, v66, v67
	s_nop 1
	v_mov_b32_dpp v67, v66 quad_perm:[2,3,0,1] row_mask:0xf bank_mask:0xf
	s_waitcnt lgkmcnt(0)
	v_add_f32_e32 v66, v66, v67
	s_nop 1
	v_mov_b32_dpp v67, v66 row_half_mirror row_mask:0xf bank_mask:0xf
	s_waitcnt lgkmcnt(0)
	v_add_f32_e32 v66, v66, v67
	s_nop 1
	v_mov_b32_dpp v67, v66 row_mirror row_mask:0xf bank_mask:0xf
	s_and_saveexec_b64 s[4:5], s[40:41]
	s_cbranch_execz .LBB0_417
	s_waitcnt lgkmcnt(0)
	v_add_f32_e32 v66, v66, v67
	ds_write_b32 v110, v66 offset:76

.LBB0_418:
	s_and_b64 vcc, exec, s[38:39]
	v_or_b32_e32 v99, 32, v135
	s_cbranch_vccnz .LBB0_428
	s_waitcnt lgkmcnt(0)
	ds_read_b128 v[66:69], v94 offset:16896
	ds_read_b128 v[90:93], v94 offset:16960
	s_waitcnt lgkmcnt(1)
	v_mfma_f32_16x16x32_bf16 v[70:73], v[66:69], v[0:3], 0
	v_mfma_f32_16x16x32_bf16 v[66:69], v[66:69], v[4:7], 0
	s_waitcnt lgkmcnt(0)
	v_mfma_f32_16x16x32_bf16 v[70:73], v[90:93], v[8:11], v[70:73]
	v_mfma_f32_16x16x32_bf16 v[66:69], v[90:93], v[12:15], v[66:69]
	ds_read_b128 v[90:93], v94 offset:17024
	s_waitcnt lgkmcnt(0)
	v_mfma_f32_16x16x32_bf16 v[70:73], v[90:93], v[16:19], v[70:73]
	v_mfma_f32_16x16x32_bf16 v[66:69], v[90:93], v[22:25], v[66:69]
	ds_read_b128 v[90:93], v94 offset:17088
	s_waitcnt lgkmcnt(0)
	v_mfma_f32_16x16x32_bf16 v[70:73], v[90:93], v[26:29], v[70:73]
	v_mfma_f32_16x16x32_bf16 v[66:69], v[90:93], v[30:33], v[66:69]
	ds_read_b128 v[90:93], v94 offset:17152
	s_waitcnt lgkmcnt(0)
	v_mfma_f32_16x16x32_bf16 v[70:73], v[90:93], v[34:37], v[70:73]
	v_mfma_f32_16x16x32_bf16 v[66:69], v[90:93], v[38:41], v[66:69]
	ds_read_b128 v[90:93], v94 offset:17216
	s_waitcnt lgkmcnt(0)
	v_mfma_f32_16x16x32_bf16 v[70:73], v[90:93], v[42:45], v[70:73]
	v_mfma_f32_16x16x32_bf16 v[66:69], v[90:93], v[46:49], v[66:69]
	ds_read_b128 v[90:93], v94 offset:17280
	s_waitcnt lgkmcnt(0)
	v_mfma_f32_16x16x32_bf16 v[70:73], v[90:93], v[50:53], v[70:73]
	v_mfma_f32_16x16x32_bf16 v[66:69], v[90:93], v[54:57], v[66:69]
	ds_read_b128 v[90:93], v94 offset:17344
	s_waitcnt lgkmcnt(0)
	v_mfma_f32_16x16x32_bf16 v[70:73], v[90:93], v[58:61], v[70:73]
	s_nop 7
	v_mul_f32_e32 v70, 0xbfb8aa3b, v70
	v_mfma_f32_16x16x32_bf16 v[66:69], v[90:93], v[62:65], v[66:69]
	v_exp_f32_e32 v70, v70
	v_mul_u32_u24_e32 v90, 0x210, v99
	v_add3_u32 v91, v83, v90, v78
	v_add_f32_e32 v70, 1.0, v70
	v_rcp_f32_e32 v93, v70
	s_nop 2
	v_mul_f32_e32 v66, 0xbfb8aa3b, v66
	v_exp_f32_e32 v66, v66
	s_nop 0
	v_add_f32_e32 v66, 1.0, v66
	v_rcp_f32_e32 v92, v66
	ds_read_u16 v66, v91
	ds_read_u16 v70, v91 offset:32
	s_waitcnt lgkmcnt(1)
	v_lshlrev_b32_e32 v97, 16, v66
	s_waitcnt lgkmcnt(0)
	v_lshlrev_b32_e32 v96, 16, v70
	v_pk_mul_f32 v[92:93], v[92:93], v[96:97]
	s_nop 0
	v_pk_mul_f32 v[96:97], v[92:93], v[92:93]
	s_nop 0
	v_add_f32_e32 v66, v97, v96
	s_nop 1
	v_mov_b32_dpp v70, v66 quad_perm:[1,0,3,2] row_mask:0xf bank_mask:0xf
	s_waitcnt lgkmcnt(0)
	v_add_f32_e32 v66, v66, v70
	s_nop 1
	v_mov_b32_dpp v70, v66 quad_perm:[2,3,0,1] row_mask:0xf bank_mask:0xf
	s_waitcnt lgkmcnt(0)
	v_add_f32_e32 v66, v66, v70
	s_nop 1
	v_mov_b32_dpp v70, v66 row_half_mirror row_mask:0xf bank_mask:0xf
	s_waitcnt lgkmcnt(0)
	v_add_f32_e32 v66, v66, v70
	s_nop 1
	v_mov_b32_dpp v70, v66 row_mirror row_mask:0xf bank_mask:0xf
	s_and_saveexec_b64 s[4:5], s[40:41]
	s_cbranch_execz .LBB0_421
	s_waitcnt lgkmcnt(0)
	v_add_f32_e32 v66, v66, v70
	ds_write_b32 v110, v66 offset:128
.LBB0_421:
	s_or_b64 exec, exec, s[4:5]
	v_mul_f32_e32 v66, 0xbfb8aa3b, v71
	v_mul_f32_e32 v67, 0xbfb8aa3b, v67
	s_waitcnt lgkmcnt(0)
	v_exp_f32_e32 v70, v66
	v_exp_f32_e32 v67, v67
	v_add_u32_e32 v66, 0x210, v90
	v_add3_u32 v90, v83, v66, v78
	ds_read_u16 v91, v90
	ds_read_u16 v90, v90 offset:32
	v_add_f32_e32 v70, 1.0, v70
	v_add_f32_e32 v67, 1.0, v67
	v_rcp_f32_e32 v71, v70
	v_rcp_f32_e32 v70, v67
	s_waitcnt lgkmcnt(1)
	v_lshlrev_b32_e32 v91, 16, v91
	s_waitcnt lgkmcnt(0)
	v_lshlrev_b32_e32 v90, 16, v90
	v_pk_mul_f32 v[90:91], v[70:71], v[90:91]
	s_nop 0
	v_pk_mul_f32 v[70:71], v[90:91], v[90:91]
	s_nop 0
	v_add_f32_e32 v67, v71, v70
	s_nop 1
	v_mov_b32_dpp v70, v67 quad_perm:[1,0,3,2] row_mask:0xf bank_mask:0xf
	s_waitcnt lgkmcnt(0)
	v_add_f32_e32 v67, v67, v70
	s_nop 1
	v_mov_b32_dpp v70, v67 quad_perm:[2,3,0,1] row_mask:0xf bank_mask:0xf
	s_waitcnt lgkmcnt(0)
	v_add_f32_e32 v67, v67, v70
	s_nop 1
	v_mov_b32_dpp v70, v67 row_half_mirror row_mask:0xf bank_mask:0xf
	s_waitcnt lgkmcnt(0)
	v_add_f32_e32 v67, v67, v70
	s_nop 1
	v_mov_b32_dpp v70, v67 row_mirror row_mask:0xf bank_mask:0xf
	s_and_saveexec_b64 s[4:5], s[40:41]
	s_cbranch_execz .LBB0_423
	s_waitcnt lgkmcnt(0)
	v_add_f32_e32 v67, v67, v70
	ds_write_b32 v110, v67 offset:132
.LBB0_423:
	s_or_b64 exec, exec, s[4:5]
	v_mul_f32_e32 v67, 0xbfb8aa3b, v72
	v_exp_f32_e32 v67, v67
	v_mul_f32_e32 v68, 0xbfb8aa3b, v68
	v_exp_f32_e32 v68, v68
	v_add_u32_e32 v66, 0x210, v66
	v_add3_u32 v66, v83, v66, v78
	v_add_f32_e32 v67, 1.0, v67
	v_rcp_f32_e32 v71, v67
	ds_read_u16 v67, v66
	ds_read_u16 v72, v66 offset:32
	v_add_f32_e32 v68, 1.0, v68
	s_waitcnt lgkmcnt(2)
	v_rcp_f32_e32 v70, v68
	s_waitcnt lgkmcnt(1)
	v_lshlrev_b32_e32 v97, 16, v67
	s_waitcnt lgkmcnt(0)
	v_lshlrev_b32_e32 v96, 16, v72
	v_pk_mul_f32 v[70:71], v[70:71], v[96:97]
	s_nop 0
	v_pk_mul_f32 v[96:97], v[70:71], v[70:71]
	s_nop 0
	v_add_f32_e32 v67, v97, v96
	s_nop 1
	v_mov_b32_dpp v68, v67 quad_perm:[1,0,3,2] row_mask:0xf bank_mask:0xf
	s_waitcnt lgkmcnt(0)
	v_add_f32_e32 v67, v67, v68
	s_nop 1
	v_mov_b32_dpp v68, v67 quad_perm:[2,3,0,1] row_mask:0xf bank_mask:0xf
	s_waitcnt lgkmcnt(0)
	v_add_f32_e32 v67, v67, v68
	s_nop 1
	v_mov_b32_dpp v68, v67 row_half_mirror row_mask:0xf bank_mask:0xf
	s_waitcnt lgkmcnt(0)
	v_add_f32_e32 v67, v67, v68
	s_nop 1
	v_mov_b32_dpp v68, v67 row_mirror row_mask:0xf bank_mask:0xf
	s_and_saveexec_b64 s[4:5], s[40:41]
	s_cbranch_execz .LBB0_425
	s_waitcnt lgkmcnt(0)
	v_add_f32_e32 v67, v67, v68
	ds_write_b32 v110, v67 offset:136
.LBB0_425:
	s_or_b64 exec, exec, s[4:5]
	v_mul_f32_e32 v67, 0xbfb8aa3b, v73
	s_waitcnt lgkmcnt(0)
	v_mul_f32_e32 v68, 0xbfb8aa3b, v69
	v_exp_f32_e32 v67, v67
	v_exp_f32_e32 v68, v68
	ds_read_u16 v69, v66 offset:528
	ds_read_u16 v72, v66 offset:560
	v_add_f32_e32 v67, 1.0, v67
	v_add_f32_e32 v66, 1.0, v68
	v_rcp_f32_e32 v67, v67
	v_rcp_f32_e32 v66, v66
	s_waitcnt lgkmcnt(1)
	v_lshlrev_b32_e32 v69, 16, v69
	s_waitcnt lgkmcnt(0)
	v_lshlrev_b32_e32 v68, 16, v72
	v_pk_mul_f32 v[66:67], v[66:67], v[68:69]
	s_nop 0
	v_pk_mul_f32 v[68:69], v[66:67], v[66:67]
	s_nop 0
	v_add_f32_e32 v68, v69, v68
	s_nop 1
	v_mov_b32_dpp v69, v68 quad_perm:[1,0,3,2] row_mask:0xf bank_mask:0xf
	s_waitcnt lgkmcnt(0)
	v_add_f32_e32 v68, v68, v69
	s_nop 1
	v_mov_b32_dpp v69, v68 quad_perm:[2,3,0,1] row_mask:0xf bank_mask:0xf
	s_waitcnt lgkmcnt(0)
	v_add_f32_e32 v68, v68, v69
	s_nop 1
	v_mov_b32_dpp v69, v68 row_half_mirror row_mask:0xf bank_mask:0xf
	s_waitcnt lgkmcnt(0)
	v_add_f32_e32 v68, v68, v69
	s_nop 1
	v_mov_b32_dpp v69, v68 row_mirror row_mask:0xf bank_mask:0xf
	s_and_saveexec_b64 s[4:5], s[40:41]
	s_cbranch_execz .LBB0_427
	s_waitcnt lgkmcnt(0)
	v_add_f32_e32 v68, v68, v69
	ds_write_b32 v110, v68 offset:140

.LBB0_428:
	s_and_b64 vcc, exec, s[38:39]
	v_or_b32_e32 v102, 48, v135
	s_cbranch_vccnz .LBB0_438
	ds_read_b128 v[112:115], v94 offset:25344
	s_waitcnt lgkmcnt(0)
	v_mfma_f32_16x16x32_bf16 v[0:3], v[112:115], v[0:3], 0
	v_mfma_f32_16x16x32_bf16 v[4:7], v[112:115], v[4:7], 0
	ds_read_b128 v[112:115], v94 offset:25408
	s_waitcnt lgkmcnt(0)
	v_mfma_f32_16x16x32_bf16 v[0:3], v[112:115], v[8:11], v[0:3]
	ds_read_b128 v[8:11], v94 offset:25472
	v_mfma_f32_16x16x32_bf16 v[4:7], v[112:115], v[12:15], v[4:7]
	ds_read_b128 v[12:15], v94 offset:25792
	s_waitcnt lgkmcnt(1)
	v_mfma_f32_16x16x32_bf16 v[0:3], v[8:11], v[16:19], v[0:3]
	v_mfma_f32_16x16x32_bf16 v[4:7], v[8:11], v[22:25], v[4:7]
	ds_read_b128 v[8:11], v94 offset:25536
	s_waitcnt lgkmcnt(0)
	v_mfma_f32_16x16x32_bf16 v[0:3], v[8:11], v[26:29], v[0:3]
	v_mfma_f32_16x16x32_bf16 v[4:7], v[8:11], v[30:33], v[4:7]
	ds_read_b128 v[8:11], v94 offset:25600
	s_waitcnt lgkmcnt(0)
	v_mfma_f32_16x16x32_bf16 v[0:3], v[8:11], v[34:37], v[0:3]
	v_mfma_f32_16x16x32_bf16 v[4:7], v[8:11], v[38:41], v[4:7]
	ds_read_b128 v[8:11], v94 offset:25664
	s_waitcnt lgkmcnt(0)
	v_mfma_f32_16x16x32_bf16 v[0:3], v[8:11], v[42:45], v[0:3]
	v_mfma_f32_16x16x32_bf16 v[4:7], v[8:11], v[46:49], v[4:7]
	ds_read_b128 v[8:11], v94 offset:25728
	s_waitcnt lgkmcnt(0)
	v_mfma_f32_16x16x32_bf16 v[0:3], v[8:11], v[50:53], v[0:3]
	v_mfma_f32_16x16x32_bf16 v[8:11], v[8:11], v[54:57], v[4:7]
	v_mfma_f32_16x16x32_bf16 v[4:7], v[12:15], v[58:61], v[0:3]
	v_mfma_f32_16x16x32_bf16 v[0:3], v[12:15], v[62:65], v[8:11]
	s_nop 5
	v_mul_u32_u24_e32 v8, 0x210, v102
	v_mul_f32_e32 v4, 0xbfb8aa3b, v4
	v_mul_f32_e32 v0, 0xbfb8aa3b, v0
	v_exp_f32_e32 v4, v4
	v_exp_f32_e32 v0, v0
	v_add3_u32 v9, v83, v8, v78
	v_add_f32_e32 v4, 1.0, v4
	v_add_f32_e32 v0, 1.0, v0
	v_rcp_f32_e32 v11, v4
	v_rcp_f32_e32 v10, v0
	ds_read_u16 v0, v9
	ds_read_u16 v4, v9 offset:32
	s_waitcnt lgkmcnt(1)
	v_lshlrev_b32_e32 v13, 16, v0
	s_waitcnt lgkmcnt(0)
	v_lshlrev_b32_e32 v12, 16, v4
	v_pk_mul_f32 v[96:97], v[10:11], v[12:13]
	s_nop 0
	v_pk_mul_f32 v[10:11], v[96:97], v[96:97]
	s_nop 0
	v_add_f32_e32 v0, v11, v10
	s_nop 1
	v_mov_b32_dpp v4, v0 quad_perm:[1,0,3,2] row_mask:0xf bank_mask:0xf
	s_waitcnt lgkmcnt(0)
	v_add_f32_e32 v0, v0, v4
	s_nop 1
	v_mov_b32_dpp v4, v0 quad_perm:[2,3,0,1] row_mask:0xf bank_mask:0xf
	s_waitcnt lgkmcnt(0)
	v_add_f32_e32 v0, v0, v4
	s_nop 1
	v_mov_b32_dpp v4, v0 row_half_mirror row_mask:0xf bank_mask:0xf
	s_waitcnt lgkmcnt(0)
	v_add_f32_e32 v0, v0, v4
	s_nop 1
	v_mov_b32_dpp v4, v0 row_mirror row_mask:0xf bank_mask:0xf
	s_and_saveexec_b64 s[4:5], s[40:41]
	s_cbranch_execz .LBB0_431
	s_waitcnt lgkmcnt(0)
	v_add_f32_e32 v0, v0, v4
	ds_write_b32 v110, v0 offset:192
.LBB0_431:
	s_or_b64 exec, exec, s[4:5]
	v_mul_f32_e32 v0, 0xbfb8aa3b, v5
	v_mul_f32_e32 v1, 0xbfb8aa3b, v1
	s_waitcnt lgkmcnt(0)
	v_exp_f32_e32 v4, v0
	v_exp_f32_e32 v1, v1
	v_add_u32_e32 v0, 0x210, v8
	v_add3_u32 v8, v83, v0, v78
	ds_read_u16 v9, v8
	ds_read_u16 v8, v8 offset:32
	v_add_f32_e32 v4, 1.0, v4
	v_add_f32_e32 v1, 1.0, v1
	v_rcp_f32_e32 v5, v4
	v_rcp_f32_e32 v4, v1
	s_waitcnt lgkmcnt(1)
	v_lshlrev_b32_e32 v9, 16, v9
	s_waitcnt lgkmcnt(0)
	v_lshlrev_b32_e32 v8, 16, v8
	v_pk_mul_f32 v[94:95], v[4:5], v[8:9]
	s_nop 0
	v_pk_mul_f32 v[4:5], v[94:95], v[94:95]
	s_nop 0
	v_add_f32_e32 v1, v5, v4
	s_nop 1
	v_mov_b32_dpp v4, v1 quad_perm:[1,0,3,2] row_mask:0xf bank_mask:0xf
	s_waitcnt lgkmcnt(0)
	v_add_f32_e32 v1, v1, v4
	s_nop 1
	v_mov_b32_dpp v4, v1 quad_perm:[2,3,0,1] row_mask:0xf bank_mask:0xf
	s_waitcnt lgkmcnt(0)
	v_add_f32_e32 v1, v1, v4
	s_nop 1
	v_mov_b32_dpp v4, v1 row_half_mirror row_mask:0xf bank_mask:0xf
	s_waitcnt lgkmcnt(0)
	v_add_f32_e32 v1, v1, v4
	s_nop 1
	v_mov_b32_dpp v4, v1 row_mirror row_mask:0xf bank_mask:0xf
	s_and_saveexec_b64 s[4:5], s[40:41]
	s_cbranch_execz .LBB0_433
	s_waitcnt lgkmcnt(0)
	v_add_f32_e32 v1, v1, v4
	ds_write_b32 v110, v1 offset:196
.LBB0_433:
	s_or_b64 exec, exec, s[4:5]
	v_mul_f32_e32 v1, 0xbfb8aa3b, v6
	v_exp_f32_e32 v1, v1
	v_mul_f32_e32 v2, 0xbfb8aa3b, v2
	v_exp_f32_e32 v2, v2
	v_add_u32_e32 v0, 0x210, v0
	v_add3_u32 v0, v83, v0, v78
	v_add_f32_e32 v1, 1.0, v1
	v_rcp_f32_e32 v5, v1
	ds_read_u16 v1, v0
	ds_read_u16 v6, v0 offset:32
	v_add_f32_e32 v2, 1.0, v2
	s_waitcnt lgkmcnt(2)
	v_rcp_f32_e32 v4, v2
	s_waitcnt lgkmcnt(1)
	v_lshlrev_b32_e32 v9, 16, v1
	s_waitcnt lgkmcnt(0)
	v_lshlrev_b32_e32 v8, 16, v6
	v_pk_mul_f32 v[72:73], v[4:5], v[8:9]
	s_nop 0
	v_pk_mul_f32 v[4:5], v[72:73], v[72:73]
	s_nop 0
	v_add_f32_e32 v1, v5, v4
	s_nop 1
	v_mov_b32_dpp v2, v1 quad_perm:[1,0,3,2] row_mask:0xf bank_mask:0xf
	s_waitcnt lgkmcnt(0)
	v_add_f32_e32 v1, v1, v2
	s_nop 1
	v_mov_b32_dpp v2, v1 quad_perm:[2,3,0,1] row_mask:0xf bank_mask:0xf
	s_waitcnt lgkmcnt(0)
	v_add_f32_e32 v1, v1, v2
	s_nop 1
	v_mov_b32_dpp v2, v1 row_half_mirror row_mask:0xf bank_mask:0xf
	s_waitcnt lgkmcnt(0)
	v_add_f32_e32 v1, v1, v2
	s_nop 1
	v_mov_b32_dpp v2, v1 row_mirror row_mask:0xf bank_mask:0xf
	s_and_saveexec_b64 s[4:5], s[40:41]
	s_cbranch_execz .LBB0_435
	s_waitcnt lgkmcnt(0)
	v_add_f32_e32 v1, v1, v2
	ds_write_b32 v110, v1 offset:200
.LBB0_435:
	s_or_b64 exec, exec, s[4:5]
	v_mul_f32_e32 v1, 0xbfb8aa3b, v7
	s_waitcnt lgkmcnt(0)
	v_mul_f32_e32 v2, 0xbfb8aa3b, v3
	v_exp_f32_e32 v1, v1
	v_exp_f32_e32 v2, v2
	ds_read_u16 v3, v0 offset:528
	ds_read_u16 v4, v0 offset:560
	v_add_f32_e32 v1, 1.0, v1
	v_add_f32_e32 v0, 1.0, v2
	v_rcp_f32_e32 v1, v1
	v_rcp_f32_e32 v0, v0
	s_waitcnt lgkmcnt(1)
	v_lshlrev_b32_e32 v3, 16, v3
	s_waitcnt lgkmcnt(0)
	v_lshlrev_b32_e32 v2, 16, v4
	v_pk_mul_f32 v[68:69], v[0:1], v[2:3]
	s_nop 0
	v_pk_mul_f32 v[0:1], v[68:69], v[68:69]
	s_nop 0
	v_add_f32_e32 v0, v1, v0
	s_nop 1
	v_mov_b32_dpp v1, v0 quad_perm:[1,0,3,2] row_mask:0xf bank_mask:0xf
	s_waitcnt lgkmcnt(0)
	v_add_f32_e32 v0, v0, v1
	s_nop 1
	v_mov_b32_dpp v1, v0 quad_perm:[2,3,0,1] row_mask:0xf bank_mask:0xf
	s_waitcnt lgkmcnt(0)
	v_add_f32_e32 v0, v0, v1
	s_nop 1
	v_mov_b32_dpp v1, v0 row_half_mirror row_mask:0xf bank_mask:0xf
	s_waitcnt lgkmcnt(0)
	v_add_f32_e32 v0, v0, v1
	s_nop 1
	v_mov_b32_dpp v1, v0 row_mirror row_mask:0xf bank_mask:0xf
	s_and_saveexec_b64 s[4:5], s[40:41]
	s_cbranch_execz .LBB0_437
	s_waitcnt lgkmcnt(0)
	v_add_f32_e32 v0, v0, v1
	ds_write_b32 v110, v0 offset:204

.LBB0_525:
	v_lshlrev_b32_e32 v82, 5, v136
	v_or_b32_e32 v34, v82, v76
	v_lshlrev_b32_e32 v0, 1, v80
	v_mov_b32_e32 v1, v20
	v_ashrrev_i32_e32 v35, 31, v34
	v_lshl_add_u64 v[36:37], s[86:87], 0, v[0:1]
	v_lshlrev_b64 v[0:1], 9, v[34:35]
	v_or_b32_e32 v34, 16, v34
	v_ashrrev_i32_e32 v35, 31, v34
	v_lshlrev_b64 v[34:35], 9, v[34:35]
	v_lshl_add_u64 v[0:1], v[36:37], 0, v[0:1]
	v_lshl_add_u64 v[34:35], v[36:37], 0, v[34:35]
	s_waitcnt lgkmcnt(0)
	s_barrier
	global_load_dwordx4 v[30:33], v[0:1], off
	global_load_dwordx4 v[26:29], v[0:1], off offset:64
	global_load_dwordx4 v[22:25], v[0:1], off offset:128
	global_load_dwordx4 v[16:19], v[0:1], off offset:192
	global_load_dwordx4 v[12:15], v[0:1], off offset:256
	global_load_dwordx4 v[8:11], v[0:1], off offset:320
	global_load_dwordx4 v[4:7], v[0:1], off offset:384
	s_nop 0
	global_load_dwordx4 v[0:3], v[0:1], off offset:448
	s_nop 0
	global_load_dwordx4 v[62:65], v[34:35], off
	global_load_dwordx4 v[58:61], v[34:35], off offset:64
	global_load_dwordx4 v[54:57], v[34:35], off offset:128
	global_load_dwordx4 v[50:53], v[34:35], off offset:192
	global_load_dwordx4 v[46:49], v[34:35], off offset:256
	global_load_dwordx4 v[42:45], v[34:35], off offset:320
	global_load_dwordx4 v[38:41], v[34:35], off offset:384
	s_nop 0
	global_load_dwordx4 v[34:37], v[34:35], off offset:448
	v_and_b32_e32 v66, 48, v81
	v_readlane_b32 s4, v255, 5
	v_cmp_eq_u32_e64 s[40:41], 0, v76
	s_nop 0
	v_add_u32_e32 v80, s4, v66
	v_and_b32_e32 v66, 0xffffffc0, v81
	v_add_u32_e32 v83, s4, v66
	s_movk_i32 s4, 0x210
	v_mad_u32_u24 v88, v76, s4, v80
	v_lshl_add_u32 v81, v66, 2, s66
	ds_read_b128 v[66:69], v88
	ds_read_b128 v[84:87], v88 offset:64
	v_add3_u32 v79, v83, v79, v78
	v_lshl_add_u32 v109, v135, 2, v81
	s_waitcnt vmcnt(15) lgkmcnt(1)
	v_mfma_f32_16x16x32_bf16 v[70:73], v[66:69], v[30:33], 0
	s_waitcnt vmcnt(7)
	v_mfma_f32_16x16x32_bf16 v[66:69], v[66:69], v[62:65], 0
	s_waitcnt lgkmcnt(0)
	v_mfma_f32_16x16x32_bf16 v[70:73], v[84:87], v[26:29], v[70:73]
	s_waitcnt vmcnt(6)
	v_mfma_f32_16x16x32_bf16 v[66:69], v[84:87], v[58:61], v[66:69]
	ds_read_b128 v[84:87], v88 offset:128
	s_waitcnt lgkmcnt(0)
	v_mfma_f32_16x16x32_bf16 v[70:73], v[84:87], v[22:25], v[70:73]
	s_waitcnt vmcnt(5)
	v_mfma_f32_16x16x32_bf16 v[66:69], v[84:87], v[54:57], v[66:69]
	ds_read_b128 v[84:87], v88 offset:192
	s_waitcnt lgkmcnt(0)
	v_mfma_f32_16x16x32_bf16 v[70:73], v[84:87], v[16:19], v[70:73]
	s_waitcnt vmcnt(4)
	v_mfma_f32_16x16x32_bf16 v[66:69], v[84:87], v[50:53], v[66:69]
	ds_read_b128 v[84:87], v88 offset:256
	s_waitcnt lgkmcnt(0)
	v_mfma_f32_16x16x32_bf16 v[70:73], v[84:87], v[12:15], v[70:73]
	s_waitcnt vmcnt(3)
	v_mfma_f32_16x16x32_bf16 v[66:69], v[84:87], v[46:49], v[66:69]
	ds_read_b128 v[84:87], v88 offset:320
	s_waitcnt lgkmcnt(0)
	v_mfma_f32_16x16x32_bf16 v[70:73], v[84:87], v[8:11], v[70:73]
	s_waitcnt vmcnt(2)
	v_mfma_f32_16x16x32_bf16 v[66:69], v[84:87], v[42:45], v[66:69]
	ds_read_b128 v[84:87], v88 offset:384
	s_waitcnt lgkmcnt(0)
	v_mfma_f32_16x16x32_bf16 v[70:73], v[84:87], v[4:7], v[70:73]
	s_waitcnt vmcnt(1)
	v_mfma_f32_16x16x32_bf16 v[66:69], v[84:87], v[38:41], v[66:69]
	ds_read_b128 v[84:87], v88 offset:448
	s_waitcnt vmcnt(0) lgkmcnt(0)
	v_mfma_f32_16x16x32_bf16 v[66:69], v[84:87], v[34:37], v[66:69]
	s_nop 7
	v_mul_f32_e32 v66, 0xbfb8aa3b, v66
	v_mfma_f32_16x16x32_bf16 v[70:73], v[84:87], v[0:3], v[70:73]
	v_exp_f32_e32 v66, v66
	ds_read_u16 v84, v79
	ds_read_u16 v79, v79 offset:32
	v_add_f32_e32 v66, 1.0, v66
	v_rcp_f32_e32 v66, v66
	s_nop 2
	v_mul_f32_e32 v70, 0xbfb8aa3b, v70
	v_exp_f32_e32 v70, v70
	s_waitcnt lgkmcnt(0)
	v_lshlrev_b32_e32 v79, 16, v79
	v_lshlrev_b32_e32 v84, 16, v84
	v_mul_f32_e32 v108, v66, v79
	v_add_f32_e32 v70, 1.0, v70
	v_rcp_f32_e32 v70, v70
	v_mul_f32_e32 v66, v108, v108
	v_mul_f32_e32 v107, v70, v84
	v_fmac_f32_e32 v66, v107, v107
	s_nop 1
	v_mov_b32_dpp v70, v66 quad_perm:[1,0,3,2] row_mask:0xf bank_mask:0xf
	s_waitcnt lgkmcnt(0)
	v_add_f32_e32 v66, v66, v70
	s_nop 1
	v_mov_b32_dpp v70, v66 quad_perm:[2,3,0,1] row_mask:0xf bank_mask:0xf
	s_waitcnt lgkmcnt(0)
	v_add_f32_e32 v66, v66, v70
	s_nop 1
	v_mov_b32_dpp v70, v66 row_half_mirror row_mask:0xf bank_mask:0xf
	s_waitcnt lgkmcnt(0)
	v_add_f32_e32 v66, v66, v70
	s_nop 1
	v_mov_b32_dpp v70, v66 row_mirror row_mask:0xf bank_mask:0xf
	s_and_saveexec_b64 s[4:5], s[40:41]
	s_cbranch_execz .LBB0_527
	s_waitcnt lgkmcnt(0)
	v_add_f32_e32 v66, v66, v70
	ds_write_b32 v109, v66
.LBB0_527:
	s_or_b64 exec, exec, s[4:5]
	v_mul_f32_e32 v67, 0xbfb8aa3b, v67
	v_or_b32_e32 v104, 1, v135
	v_mul_f32_e32 v71, 0xbfb8aa3b, v71
	v_exp_f32_e32 v67, v67
	v_mul_u32_u24_e32 v66, 0x210, v104
	v_exp_f32_e32 v71, v71
	s_waitcnt lgkmcnt(0)
	v_add3_u32 v70, v83, v66, v78
	ds_read_u16 v79, v70
	ds_read_u16 v70, v70 offset:32
	v_add_f32_e32 v67, 1.0, v67
	v_add_f32_e32 v71, 1.0, v71
	v_rcp_f32_e32 v67, v67
	v_rcp_f32_e32 v71, v71
	s_waitcnt lgkmcnt(0)
	v_lshlrev_b32_e32 v70, 16, v70
	v_lshlrev_b32_e32 v79, 16, v79
	v_mul_f32_e32 v105, v67, v70
	v_mul_f32_e32 v106, v71, v79
	v_mul_f32_e32 v67, v105, v105
	v_fmac_f32_e32 v67, v106, v106
	s_nop 1
	v_mov_b32_dpp v70, v67 quad_perm:[1,0,3,2] row_mask:0xf bank_mask:0xf
	s_waitcnt lgkmcnt(0)
	v_add_f32_e32 v67, v67, v70
	s_nop 1
	v_mov_b32_dpp v70, v67 quad_perm:[2,3,0,1] row_mask:0xf bank_mask:0xf
	s_waitcnt lgkmcnt(0)
	v_add_f32_e32 v67, v67, v70
	s_nop 1
	v_mov_b32_dpp v70, v67 row_half_mirror row_mask:0xf bank_mask:0xf
	s_waitcnt lgkmcnt(0)
	v_add_f32_e32 v67, v67, v70
	s_nop 1
	v_mov_b32_dpp v70, v67 row_mirror row_mask:0xf bank_mask:0xf
	s_and_saveexec_b64 s[4:5], s[40:41]
	s_cbranch_execz .LBB0_529
	s_waitcnt lgkmcnt(0)
	v_add_f32_e32 v67, v67, v70
	ds_write_b32 v109, v67 offset:4
.LBB0_529:
	s_or_b64 exec, exec, s[4:5]
	v_mul_f32_e32 v68, 0xbfb8aa3b, v68
	v_mul_f32_e32 v67, 0xbfb8aa3b, v72
	v_exp_f32_e32 v68, v68
	v_add_u32_e32 v66, 0x210, v66
	v_exp_f32_e32 v67, v67
	v_add3_u32 v66, v83, v66, v78
	s_waitcnt lgkmcnt(0)
	ds_read_u16 v70, v66
	ds_read_u16 v71, v66 offset:32
	v_add_f32_e32 v68, 1.0, v68
	v_add_f32_e32 v67, 1.0, v67
	v_rcp_f32_e32 v68, v68
	v_rcp_f32_e32 v67, v67
	s_waitcnt lgkmcnt(0)
	v_lshlrev_b32_e32 v71, 16, v71
	v_lshlrev_b32_e32 v70, 16, v70
	v_mul_f32_e32 v102, v68, v71
	v_mul_f32_e32 v103, v67, v70
	v_mul_f32_e32 v67, v102, v102
	v_fmac_f32_e32 v67, v103, v103
	s_nop 1
	v_mov_b32_dpp v68, v67 quad_perm:[1,0,3,2] row_mask:0xf bank_mask:0xf
	s_waitcnt lgkmcnt(0)
	v_add_f32_e32 v67, v67, v68
	s_nop 1
	v_mov_b32_dpp v68, v67 quad_perm:[2,3,0,1] row_mask:0xf bank_mask:0xf
	s_waitcnt lgkmcnt(0)
	v_add_f32_e32 v67, v67, v68
	s_nop 1
	v_mov_b32_dpp v68, v67 row_half_mirror row_mask:0xf bank_mask:0xf
	s_waitcnt lgkmcnt(0)
	v_add_f32_e32 v67, v67, v68
	s_nop 1
	v_mov_b32_dpp v68, v67 row_mirror row_mask:0xf bank_mask:0xf
	s_and_saveexec_b64 s[4:5], s[40:41]
	s_cbranch_execz .LBB0_531
	s_waitcnt lgkmcnt(0)
	v_add_f32_e32 v67, v67, v68
	ds_write_b32 v109, v67 offset:8
.LBB0_531:
	s_or_b64 exec, exec, s[4:5]
	s_waitcnt lgkmcnt(0)
	v_mul_f32_e32 v68, 0xbfb8aa3b, v69
	v_mul_f32_e32 v67, 0xbfb8aa3b, v73
	v_exp_f32_e32 v68, v68
	v_exp_f32_e32 v67, v67
	ds_read_u16 v69, v66 offset:528
	ds_read_u16 v66, v66 offset:560
	v_add_f32_e32 v68, 1.0, v68
	v_add_f32_e32 v67, 1.0, v67
	v_rcp_f32_e32 v68, v68
	v_rcp_f32_e32 v67, v67
	s_waitcnt lgkmcnt(0)
	v_lshlrev_b32_e32 v66, 16, v66
	v_lshlrev_b32_e32 v69, 16, v69
	v_mul_f32_e32 v99, v68, v66
	v_mul_f32_e32 v100, v67, v69
	v_mul_f32_e32 v66, v99, v99
	v_fmac_f32_e32 v66, v100, v100
	s_nop 1
	v_mov_b32_dpp v67, v66 quad_perm:[1,0,3,2] row_mask:0xf bank_mask:0xf
	s_waitcnt lgkmcnt(0)
	v_add_f32_e32 v66, v66, v67
	s_nop 1
	v_mov_b32_dpp v67, v66 quad_perm:[2,3,0,1] row_mask:0xf bank_mask:0xf
	s_waitcnt lgkmcnt(0)
	v_add_f32_e32 v66, v66, v67
	s_nop 1
	v_mov_b32_dpp v67, v66 row_half_mirror row_mask:0xf bank_mask:0xf
	s_waitcnt lgkmcnt(0)
	v_add_f32_e32 v66, v66, v67
	s_nop 1
	v_mov_b32_dpp v67, v66 row_mirror row_mask:0xf bank_mask:0xf
	s_and_saveexec_b64 s[4:5], s[40:41]
	s_cbranch_execz .LBB0_533
	s_waitcnt lgkmcnt(0)
	v_add_f32_e32 v66, v66, v67
	ds_write_b32 v109, v66 offset:12
.LBB0_533:
	s_or_b64 exec, exec, s[4:5]
	v_mul_u32_u24_e32 v66, 0x210, v76
	s_and_b64 vcc, exec, s[38:39]
	v_add_u32_e32 v94, v80, v66
	v_or_b32_e32 v79, 16, v135
	s_cbranch_vccnz .LBB0_543
	s_waitcnt lgkmcnt(0)
	ds_read_b128 v[66:69], v94 offset:8448
	ds_read_b128 v[84:87], v94 offset:8512
	v_mul_u32_u24_e32 v80, 0x210, v79
	v_add3_u32 v81, v83, v80, v78
	s_waitcnt lgkmcnt(1)
	v_mfma_f32_16x16x32_bf16 v[70:73], v[66:69], v[30:33], 0
	v_mfma_f32_16x16x32_bf16 v[66:69], v[66:69], v[62:65], 0
	s_waitcnt lgkmcnt(0)
	v_mfma_f32_16x16x32_bf16 v[70:73], v[84:87], v[26:29], v[70:73]
	v_mfma_f32_16x16x32_bf16 v[66:69], v[84:87], v[58:61], v[66:69]
	ds_read_b128 v[84:87], v94 offset:8576
	s_waitcnt lgkmcnt(0)
	v_mfma_f32_16x16x32_bf16 v[70:73], v[84:87], v[22:25], v[70:73]
	v_mfma_f32_16x16x32_bf16 v[66:69], v[84:87], v[54:57], v[66:69]
	ds_read_b128 v[84:87], v94 offset:8640
	s_waitcnt lgkmcnt(0)
	v_mfma_f32_16x16x32_bf16 v[70:73], v[84:87], v[16:19], v[70:73]
	v_mfma_f32_16x16x32_bf16 v[66:69], v[84:87], v[50:53], v[66:69]
	ds_read_b128 v[84:87], v94 offset:8704
	s_waitcnt lgkmcnt(0)
	v_mfma_f32_16x16x32_bf16 v[70:73], v[84:87], v[12:15], v[70:73]
	v_mfma_f32_16x16x32_bf16 v[66:69], v[84:87], v[46:49], v[66:69]
	ds_read_b128 v[84:87], v94 offset:8768
	s_waitcnt lgkmcnt(0)
	v_mfma_f32_16x16x32_bf16 v[70:73], v[84:87], v[8:11], v[70:73]
	v_mfma_f32_16x16x32_bf16 v[66:69], v[84:87], v[42:45], v[66:69]
	ds_read_b128 v[84:87], v94 offset:8832
	s_waitcnt lgkmcnt(0)
	v_mfma_f32_16x16x32_bf16 v[70:73], v[84:87], v[4:7], v[70:73]
	v_mfma_f32_16x16x32_bf16 v[66:69], v[84:87], v[38:41], v[66:69]
	ds_read_b128 v[84:87], v94 offset:8896
	s_waitcnt lgkmcnt(0)
	v_mfma_f32_16x16x32_bf16 v[70:73], v[84:87], v[0:3], v[70:73]
	s_nop 7
	v_mul_f32_e32 v70, 0xbfb8aa3b, v70
	v_mfma_f32_16x16x32_bf16 v[66:69], v[84:87], v[34:37], v[66:69]
	v_exp_f32_e32 v70, v70
	s_nop 0
	v_add_f32_e32 v70, 1.0, v70
	v_rcp_f32_e32 v85, v70
	s_nop 3
	v_mul_f32_e32 v66, 0xbfb8aa3b, v66
	v_exp_f32_e32 v66, v66
	s_nop 0
	v_add_f32_e32 v66, 1.0, v66
	v_rcp_f32_e32 v84, v66
	ds_read_u16 v66, v81
	ds_read_u16 v70, v81 offset:32
	s_waitcnt lgkmcnt(1)
	v_lshlrev_b32_e32 v87, 16, v66
	s_waitcnt lgkmcnt(0)
	v_lshlrev_b32_e32 v86, 16, v70
	v_pk_mul_f32 v[88:89], v[84:85], v[86:87]
	s_nop 0
	v_pk_mul_f32 v[84:85], v[88:89], v[88:89]
	s_nop 0
	v_add_f32_e32 v66, v85, v84
	s_nop 1
	v_mov_b32_dpp v70, v66 quad_perm:[1,0,3,2] row_mask:0xf bank_mask:0xf
	s_waitcnt lgkmcnt(0)
	v_add_f32_e32 v66, v66, v70
	s_nop 1
	v_mov_b32_dpp v70, v66 quad_perm:[2,3,0,1] row_mask:0xf bank_mask:0xf
	s_waitcnt lgkmcnt(0)
	v_add_f32_e32 v66, v66, v70
	s_nop 1
	v_mov_b32_dpp v70, v66 row_half_mirror row_mask:0xf bank_mask:0xf
	s_waitcnt lgkmcnt(0)
	v_add_f32_e32 v66, v66, v70
	s_nop 1
	v_mov_b32_dpp v70, v66 row_mirror row_mask:0xf bank_mask:0xf
	s_and_saveexec_b64 s[4:5], s[40:41]
	s_cbranch_execz .LBB0_536
	s_waitcnt lgkmcnt(0)
	v_add_f32_e32 v66, v66, v70
	ds_write_b32 v109, v66 offset:64
.LBB0_536:
	s_or_b64 exec, exec, s[4:5]
	v_mul_f32_e32 v66, 0xbfb8aa3b, v71
	v_mul_f32_e32 v67, 0xbfb8aa3b, v67
	s_waitcnt lgkmcnt(0)
	v_exp_f32_e32 v70, v66
	v_exp_f32_e32 v67, v67
	v_add_u32_e32 v66, 0x210, v80
	v_add3_u32 v80, v83, v66, v78
	ds_read_u16 v81, v80
	ds_read_u16 v80, v80 offset:32
	v_add_f32_e32 v70, 1.0, v70
	v_add_f32_e32 v67, 1.0, v67
	v_rcp_f32_e32 v71, v70
	v_rcp_f32_e32 v70, v67
	s_waitcnt lgkmcnt(1)
	v_lshlrev_b32_e32 v81, 16, v81
	s_waitcnt lgkmcnt(0)
	v_lshlrev_b32_e32 v80, 16, v80
	v_pk_mul_f32 v[86:87], v[70:71], v[80:81]
	s_nop 0
	v_pk_mul_f32 v[70:71], v[86:87], v[86:87]
	s_nop 0
	v_add_f32_e32 v67, v71, v70
	s_nop 1
	v_mov_b32_dpp v70, v67 quad_perm:[1,0,3,2] row_mask:0xf bank_mask:0xf
	s_waitcnt lgkmcnt(0)
	v_add_f32_e32 v67, v67, v70
	s_nop 1
	v_mov_b32_dpp v70, v67 quad_perm:[2,3,0,1] row_mask:0xf bank_mask:0xf
	s_waitcnt lgkmcnt(0)
	v_add_f32_e32 v67, v67, v70
	s_nop 1
	v_mov_b32_dpp v70, v67 row_half_mirror row_mask:0xf bank_mask:0xf
	s_waitcnt lgkmcnt(0)
	v_add_f32_e32 v67, v67, v70
	s_nop 1
	v_mov_b32_dpp v70, v67 row_mirror row_mask:0xf bank_mask:0xf
	s_and_saveexec_b64 s[4:5], s[40:41]
	s_cbranch_execz .LBB0_538
	s_waitcnt lgkmcnt(0)
	v_add_f32_e32 v67, v67, v70
	ds_write_b32 v109, v67 offset:68
.LBB0_538:
	s_or_b64 exec, exec, s[4:5]
	v_mul_f32_e32 v67, 0xbfb8aa3b, v72
	v_exp_f32_e32 v67, v67
	v_mul_f32_e32 v68, 0xbfb8aa3b, v68
	v_exp_f32_e32 v68, v68
	v_add_u32_e32 v66, 0x210, v66
	v_add3_u32 v66, v83, v66, v78
	v_add_f32_e32 v67, 1.0, v67
	v_rcp_f32_e32 v71, v67
	ds_read_u16 v67, v66
	ds_read_u16 v72, v66 offset:32
	v_add_f32_e32 v68, 1.0, v68
	s_waitcnt lgkmcnt(2)
	v_rcp_f32_e32 v70, v68
	s_waitcnt lgkmcnt(1)
	v_lshlrev_b32_e32 v81, 16, v67
	s_waitcnt lgkmcnt(0)
	v_lshlrev_b32_e32 v80, 16, v72
	v_pk_mul_f32 v[84:85], v[70:71], v[80:81]
	s_nop 0
	v_pk_mul_f32 v[70:71], v[84:85], v[84:85]
	s_nop 0
	v_add_f32_e32 v67, v71, v70
	s_nop 1
	v_mov_b32_dpp v68, v67 quad_perm:[1,0,3,2] row_mask:0xf bank_mask:0xf
	s_waitcnt lgkmcnt(0)
	v_add_f32_e32 v67, v67, v68
	s_nop 1
	v_mov_b32_dpp v68, v67 quad_perm:[2,3,0,1] row_mask:0xf bank_mask:0xf
	s_waitcnt lgkmcnt(0)
	v_add_f32_e32 v67, v67, v68
	s_nop 1
	v_mov_b32_dpp v68, v67 row_half_mirror row_mask:0xf bank_mask:0xf
	s_waitcnt lgkmcnt(0)
	v_add_f32_e32 v67, v67, v68
	s_nop 1
	v_mov_b32_dpp v68, v67 row_mirror row_mask:0xf bank_mask:0xf
	s_and_saveexec_b64 s[4:5], s[40:41]
	s_cbranch_execz .LBB0_540
	s_waitcnt lgkmcnt(0)
	v_add_f32_e32 v67, v67, v68
	ds_write_b32 v109, v67 offset:72
.LBB0_540:
	s_or_b64 exec, exec, s[4:5]
	v_mul_f32_e32 v67, 0xbfb8aa3b, v73
	s_waitcnt lgkmcnt(0)
	v_mul_f32_e32 v68, 0xbfb8aa3b, v69
	v_exp_f32_e32 v67, v67
	v_exp_f32_e32 v68, v68
	ds_read_u16 v69, v66 offset:528
	ds_read_u16 v70, v66 offset:560
	v_add_f32_e32 v67, 1.0, v67
	v_add_f32_e32 v66, 1.0, v68
	v_rcp_f32_e32 v67, v67
	v_rcp_f32_e32 v66, v66
	s_waitcnt lgkmcnt(1)
	v_lshlrev_b32_e32 v69, 16, v69
	s_waitcnt lgkmcnt(0)
	v_lshlrev_b32_e32 v68, 16, v70
	v_pk_mul_f32 v[80:81], v[66:67], v[68:69]
	s_nop 0
	v_pk_mul_f32 v[66:67], v[80:81], v[80:81]
	s_nop 0
	v_add_f32_e32 v66, v67, v66
	s_nop 1
	v_mov_b32_dpp v67, v66 quad_perm:[1,0,3,2] row_mask:0xf bank_mask:0xf
	s_waitcnt lgkmcnt(0)
	v_add_f32_e32 v66, v66, v67
	s_nop 1
	v_mov_b32_dpp v67, v66 quad_perm:[2,3,0,1] row_mask:0xf bank_mask:0xf
	s_waitcnt lgkmcnt(0)
	v_add_f32_e32 v66, v66, v67
	s_nop 1
	v_mov_b32_dpp v67, v66 row_half_mirror row_mask:0xf bank_mask:0xf
	s_waitcnt lgkmcnt(0)
	v_add_f32_e32 v66, v66, v67
	s_nop 1
	v_mov_b32_dpp v67, v66 row_mirror row_mask:0xf bank_mask:0xf
	s_and_saveexec_b64 s[4:5], s[40:41]
	s_cbranch_execz .LBB0_542
	s_waitcnt lgkmcnt(0)
	v_add_f32_e32 v66, v66, v67
	ds_write_b32 v109, v66 offset:76

.LBB0_543:
	s_and_b64 vcc, exec, s[38:39]
	v_or_b32_e32 v98, 32, v135
	s_cbranch_vccnz .LBB0_553
	s_waitcnt lgkmcnt(0)
	ds_read_b128 v[66:69], v94 offset:16896
	ds_read_b128 v[90:93], v94 offset:16960
	s_waitcnt lgkmcnt(1)
	v_mfma_f32_16x16x32_bf16 v[70:73], v[66:69], v[30:33], 0
	v_mfma_f32_16x16x32_bf16 v[66:69], v[66:69], v[62:65], 0
	s_waitcnt lgkmcnt(0)
	v_mfma_f32_16x16x32_bf16 v[70:73], v[90:93], v[26:29], v[70:73]
	v_mfma_f32_16x16x32_bf16 v[66:69], v[90:93], v[58:61], v[66:69]
	ds_read_b128 v[90:93], v94 offset:17024
	s_waitcnt lgkmcnt(0)
	v_mfma_f32_16x16x32_bf16 v[70:73], v[90:93], v[22:25], v[70:73]
	v_mfma_f32_16x16x32_bf16 v[66:69], v[90:93], v[54:57], v[66:69]
	ds_read_b128 v[90:93], v94 offset:17088
	s_waitcnt lgkmcnt(0)
	v_mfma_f32_16x16x32_bf16 v[70:73], v[90:93], v[16:19], v[70:73]
	v_mfma_f32_16x16x32_bf16 v[66:69], v[90:93], v[50:53], v[66:69]
	ds_read_b128 v[90:93], v94 offset:17152
	s_waitcnt lgkmcnt(0)
	v_mfma_f32_16x16x32_bf16 v[70:73], v[90:93], v[12:15], v[70:73]
	v_mfma_f32_16x16x32_bf16 v[66:69], v[90:93], v[46:49], v[66:69]
	ds_read_b128 v[90:93], v94 offset:17216
	s_waitcnt lgkmcnt(0)
	v_mfma_f32_16x16x32_bf16 v[70:73], v[90:93], v[8:11], v[70:73]
	v_mfma_f32_16x16x32_bf16 v[66:69], v[90:93], v[42:45], v[66:69]
	ds_read_b128 v[90:93], v94 offset:17280
	s_waitcnt lgkmcnt(0)
	v_mfma_f32_16x16x32_bf16 v[70:73], v[90:93], v[4:7], v[70:73]
	v_mfma_f32_16x16x32_bf16 v[66:69], v[90:93], v[38:41], v[66:69]
	ds_read_b128 v[90:93], v94 offset:17344
	s_waitcnt lgkmcnt(0)
	v_mfma_f32_16x16x32_bf16 v[70:73], v[90:93], v[0:3], v[70:73]
	s_nop 7
	v_mul_f32_e32 v70, 0xbfb8aa3b, v70
	v_mfma_f32_16x16x32_bf16 v[66:69], v[90:93], v[34:37], v[66:69]
	v_exp_f32_e32 v70, v70
	v_mul_u32_u24_e32 v90, 0x210, v98
	v_add3_u32 v91, v83, v90, v78
	v_add_f32_e32 v70, 1.0, v70
	v_rcp_f32_e32 v93, v70
	s_nop 2
	v_mul_f32_e32 v66, 0xbfb8aa3b, v66
	v_exp_f32_e32 v66, v66
	s_nop 0
	v_add_f32_e32 v66, 1.0, v66
	v_rcp_f32_e32 v92, v66
	ds_read_u16 v66, v91
	ds_read_u16 v70, v91 offset:32
	s_waitcnt lgkmcnt(1)
	v_lshlrev_b32_e32 v97, 16, v66
	s_waitcnt lgkmcnt(0)
	v_lshlrev_b32_e32 v96, 16, v70
	v_pk_mul_f32 v[92:93], v[92:93], v[96:97]
	s_nop 0
	v_pk_mul_f32 v[96:97], v[92:93], v[92:93]
	s_nop 0
	v_add_f32_e32 v66, v97, v96
	s_nop 1
	v_mov_b32_dpp v70, v66 quad_perm:[1,0,3,2] row_mask:0xf bank_mask:0xf
	s_waitcnt lgkmcnt(0)
	v_add_f32_e32 v66, v66, v70
	s_nop 1
	v_mov_b32_dpp v70, v66 quad_perm:[2,3,0,1] row_mask:0xf bank_mask:0xf
	s_waitcnt lgkmcnt(0)
	v_add_f32_e32 v66, v66, v70
	s_nop 1
	v_mov_b32_dpp v70, v66 row_half_mirror row_mask:0xf bank_mask:0xf
	s_waitcnt lgkmcnt(0)
	v_add_f32_e32 v66, v66, v70
	s_nop 1
	v_mov_b32_dpp v70, v66 row_mirror row_mask:0xf bank_mask:0xf
	s_and_saveexec_b64 s[4:5], s[40:41]
	s_cbranch_execz .LBB0_546
	s_waitcnt lgkmcnt(0)
	v_add_f32_e32 v66, v66, v70
	ds_write_b32 v109, v66 offset:128
.LBB0_546:
	s_or_b64 exec, exec, s[4:5]
	v_mul_f32_e32 v66, 0xbfb8aa3b, v71
	v_mul_f32_e32 v67, 0xbfb8aa3b, v67
	s_waitcnt lgkmcnt(0)
	v_exp_f32_e32 v70, v66
	v_exp_f32_e32 v67, v67
	v_add_u32_e32 v66, 0x210, v90
	v_add3_u32 v90, v83, v66, v78
	ds_read_u16 v91, v90
	ds_read_u16 v90, v90 offset:32
	v_add_f32_e32 v70, 1.0, v70
	v_add_f32_e32 v67, 1.0, v67
	v_rcp_f32_e32 v71, v70
	v_rcp_f32_e32 v70, v67
	s_waitcnt lgkmcnt(1)
	v_lshlrev_b32_e32 v91, 16, v91
	s_waitcnt lgkmcnt(0)
	v_lshlrev_b32_e32 v90, 16, v90
	v_pk_mul_f32 v[90:91], v[70:71], v[90:91]
	s_nop 0
	v_pk_mul_f32 v[70:71], v[90:91], v[90:91]
	s_nop 0
	v_add_f32_e32 v67, v71, v70
	s_nop 1
	v_mov_b32_dpp v70, v67 quad_perm:[1,0,3,2] row_mask:0xf bank_mask:0xf
	s_waitcnt lgkmcnt(0)
	v_add_f32_e32 v67, v67, v70
	s_nop 1
	v_mov_b32_dpp v70, v67 quad_perm:[2,3,0,1] row_mask:0xf bank_mask:0xf
	s_waitcnt lgkmcnt(0)
	v_add_f32_e32 v67, v67, v70
	s_nop 1
	v_mov_b32_dpp v70, v67 row_half_mirror row_mask:0xf bank_mask:0xf
	s_waitcnt lgkmcnt(0)
	v_add_f32_e32 v67, v67, v70
	s_nop 1
	v_mov_b32_dpp v70, v67 row_mirror row_mask:0xf bank_mask:0xf
	s_and_saveexec_b64 s[4:5], s[40:41]
	s_cbranch_execz .LBB0_548
	s_waitcnt lgkmcnt(0)
	v_add_f32_e32 v67, v67, v70
	ds_write_b32 v109, v67 offset:132
.LBB0_548:
	s_or_b64 exec, exec, s[4:5]
	v_mul_f32_e32 v67, 0xbfb8aa3b, v72
	v_exp_f32_e32 v67, v67
	v_mul_f32_e32 v68, 0xbfb8aa3b, v68
	v_exp_f32_e32 v68, v68
	v_add_u32_e32 v66, 0x210, v66
	v_add3_u32 v66, v83, v66, v78
	v_add_f32_e32 v67, 1.0, v67
	v_rcp_f32_e32 v71, v67
	ds_read_u16 v67, v66
	ds_read_u16 v72, v66 offset:32
	v_add_f32_e32 v68, 1.0, v68
	s_waitcnt lgkmcnt(2)
	v_rcp_f32_e32 v70, v68
	s_waitcnt lgkmcnt(1)
	v_lshlrev_b32_e32 v97, 16, v67
	s_waitcnt lgkmcnt(0)
	v_lshlrev_b32_e32 v96, 16, v72
	v_pk_mul_f32 v[70:71], v[70:71], v[96:97]
	s_nop 0
	v_pk_mul_f32 v[96:97], v[70:71], v[70:71]
	s_nop 0
	v_add_f32_e32 v67, v97, v96
	s_nop 1
	v_mov_b32_dpp v68, v67 quad_perm:[1,0,3,2] row_mask:0xf bank_mask:0xf
	s_waitcnt lgkmcnt(0)
	v_add_f32_e32 v67, v67, v68
	s_nop 1
	v_mov_b32_dpp v68, v67 quad_perm:[2,3,0,1] row_mask:0xf bank_mask:0xf
	s_waitcnt lgkmcnt(0)
	v_add_f32_e32 v67, v67, v68
	s_nop 1
	v_mov_b32_dpp v68, v67 row_half_mirror row_mask:0xf bank_mask:0xf
	s_waitcnt lgkmcnt(0)
	v_add_f32_e32 v67, v67, v68
	s_nop 1
	v_mov_b32_dpp v68, v67 row_mirror row_mask:0xf bank_mask:0xf
	s_and_saveexec_b64 s[4:5], s[40:41]
	s_cbranch_execz .LBB0_550
	s_waitcnt lgkmcnt(0)
	v_add_f32_e32 v67, v67, v68
	ds_write_b32 v109, v67 offset:136
.LBB0_550:
	s_or_b64 exec, exec, s[4:5]
	v_mul_f32_e32 v67, 0xbfb8aa3b, v73
	s_waitcnt lgkmcnt(0)
	v_mul_f32_e32 v68, 0xbfb8aa3b, v69
	v_exp_f32_e32 v67, v67
	v_exp_f32_e32 v68, v68
	ds_read_u16 v69, v66 offset:528
	ds_read_u16 v72, v66 offset:560
	v_add_f32_e32 v67, 1.0, v67
	v_add_f32_e32 v66, 1.0, v68
	v_rcp_f32_e32 v67, v67
	v_rcp_f32_e32 v66, v66
	s_waitcnt lgkmcnt(1)
	v_lshlrev_b32_e32 v69, 16, v69
	s_waitcnt lgkmcnt(0)
	v_lshlrev_b32_e32 v68, 16, v72
	v_pk_mul_f32 v[66:67], v[66:67], v[68:69]
	s_nop 0
	v_pk_mul_f32 v[68:69], v[66:67], v[66:67]
	s_nop 0
	v_add_f32_e32 v68, v69, v68
	s_nop 1
	v_mov_b32_dpp v69, v68 quad_perm:[1,0,3,2] row_mask:0xf bank_mask:0xf
	s_waitcnt lgkmcnt(0)
	v_add_f32_e32 v68, v68, v69
	s_nop 1
	v_mov_b32_dpp v69, v68 quad_perm:[2,3,0,1] row_mask:0xf bank_mask:0xf
	s_waitcnt lgkmcnt(0)
	v_add_f32_e32 v68, v68, v69
	s_nop 1
	v_mov_b32_dpp v69, v68 row_half_mirror row_mask:0xf bank_mask:0xf
	s_waitcnt lgkmcnt(0)
	v_add_f32_e32 v68, v68, v69
	s_nop 1
	v_mov_b32_dpp v69, v68 row_mirror row_mask:0xf bank_mask:0xf
	s_and_saveexec_b64 s[4:5], s[40:41]
	s_cbranch_execz .LBB0_552
	s_waitcnt lgkmcnt(0)
	v_add_f32_e32 v68, v68, v69
	ds_write_b32 v109, v68 offset:140

.LBB0_553:
	s_and_b64 vcc, exec, s[38:39]
	v_or_b32_e32 v101, 48, v135
	s_cbranch_vccnz .LBB0_563
	ds_read_b128 v[110:113], v94 offset:25344
	s_waitcnt lgkmcnt(0)
	v_mfma_f32_16x16x32_bf16 v[30:33], v[110:113], v[30:33], 0
	v_mfma_f32_16x16x32_bf16 v[62:65], v[110:113], v[62:65], 0
	ds_read_b128 v[110:113], v94 offset:25408
	s_waitcnt lgkmcnt(0)
	v_mfma_f32_16x16x32_bf16 v[26:29], v[110:113], v[26:29], v[30:33]
	v_mfma_f32_16x16x32_bf16 v[30:33], v[110:113], v[58:61], v[62:65]
	ds_read_b128 v[58:61], v94 offset:25472
	s_waitcnt lgkmcnt(0)
	v_mfma_f32_16x16x32_bf16 v[22:25], v[58:61], v[22:25], v[26:29]
	v_mfma_f32_16x16x32_bf16 v[26:29], v[58:61], v[54:57], v[30:33]
	s_nop 3
	ds_read_b128 v[30:33], v94 offset:25536
	s_waitcnt lgkmcnt(0)
	v_mfma_f32_16x16x32_bf16 v[16:19], v[30:33], v[16:19], v[22:25]
	v_mfma_f32_16x16x32_bf16 v[22:25], v[30:33], v[50:53], v[26:29]
	s_nop 2
	ds_read_b128 v[26:29], v94 offset:25600
	s_waitcnt lgkmcnt(0)
	v_mfma_f32_16x16x32_bf16 v[12:15], v[26:29], v[12:15], v[16:19]
	v_mfma_f32_16x16x32_bf16 v[16:19], v[26:29], v[46:49], v[22:25]
	s_nop 2
	ds_read_b128 v[22:25], v94 offset:25664
	s_waitcnt lgkmcnt(0)
	v_mfma_f32_16x16x32_bf16 v[8:11], v[22:25], v[8:11], v[12:15]
	v_mfma_f32_16x16x32_bf16 v[12:15], v[22:25], v[42:45], v[16:19]
	s_nop 2
	ds_read_b128 v[16:19], v94 offset:25728
	s_waitcnt lgkmcnt(0)
	v_mfma_f32_16x16x32_bf16 v[4:7], v[16:19], v[4:7], v[8:11]
	v_mfma_f32_16x16x32_bf16 v[8:11], v[16:19], v[38:41], v[12:15]
	s_nop 2
	ds_read_b128 v[12:15], v94 offset:25792
	s_waitcnt lgkmcnt(0)
	v_mfma_f32_16x16x32_bf16 v[4:7], v[12:15], v[0:3], v[4:7]
	s_nop 7
	v_mul_f32_e32 v4, 0xbfb8aa3b, v4
	v_mfma_f32_16x16x32_bf16 v[0:3], v[12:15], v[34:37], v[8:11]
	v_exp_f32_e32 v4, v4
	s_nop 0
	v_add_f32_e32 v4, 1.0, v4
	v_mul_u32_u24_e32 v8, 0x210, v101
	s_nop 3
	v_mul_f32_e32 v0, 0xbfb8aa3b, v0
	v_exp_f32_e32 v0, v0
	v_add3_u32 v9, v83, v8, v78
	v_rcp_f32_e32 v11, v4
	v_add_f32_e32 v0, 1.0, v0
	v_rcp_f32_e32 v10, v0
	ds_read_u16 v0, v9
	ds_read_u16 v4, v9 offset:32
	s_waitcnt lgkmcnt(1)
	v_lshlrev_b32_e32 v13, 16, v0
	s_waitcnt lgkmcnt(0)
	v_lshlrev_b32_e32 v12, 16, v4
	v_pk_mul_f32 v[96:97], v[10:11], v[12:13]
	s_nop 0
	v_pk_mul_f32 v[10:11], v[96:97], v[96:97]
	s_nop 0
	v_add_f32_e32 v0, v11, v10
	s_nop 1
	v_mov_b32_dpp v4, v0 quad_perm:[1,0,3,2] row_mask:0xf bank_mask:0xf
	s_waitcnt lgkmcnt(0)
	v_add_f32_e32 v0, v0, v4
	s_nop 1
	v_mov_b32_dpp v4, v0 quad_perm:[2,3,0,1] row_mask:0xf bank_mask:0xf
	s_waitcnt lgkmcnt(0)
	v_add_f32_e32 v0, v0, v4
	s_nop 1
	v_mov_b32_dpp v4, v0 row_half_mirror row_mask:0xf bank_mask:0xf
	s_waitcnt lgkmcnt(0)
	v_add_f32_e32 v0, v0, v4
	s_nop 1
	v_mov_b32_dpp v4, v0 row_mirror row_mask:0xf bank_mask:0xf
	s_and_saveexec_b64 s[4:5], s[40:41]
	s_cbranch_execz .LBB0_556
	s_waitcnt lgkmcnt(0)
	v_add_f32_e32 v0, v0, v4
	ds_write_b32 v109, v0 offset:192
.LBB0_556:
	s_or_b64 exec, exec, s[4:5]
	v_mul_f32_e32 v0, 0xbfb8aa3b, v5
	v_mul_f32_e32 v1, 0xbfb8aa3b, v1
	s_waitcnt lgkmcnt(0)
	v_exp_f32_e32 v4, v0
	v_exp_f32_e32 v1, v1
	v_add_u32_e32 v0, 0x210, v8
	v_add3_u32 v8, v83, v0, v78
	ds_read_u16 v9, v8
	ds_read_u16 v8, v8 offset:32
	v_add_f32_e32 v4, 1.0, v4
	v_add_f32_e32 v1, 1.0, v1
	v_rcp_f32_e32 v5, v4
	v_rcp_f32_e32 v4, v1
	s_waitcnt lgkmcnt(1)
	v_lshlrev_b32_e32 v9, 16, v9
	s_waitcnt lgkmcnt(0)
	v_lshlrev_b32_e32 v8, 16, v8
	v_pk_mul_f32 v[94:95], v[4:5], v[8:9]
	s_nop 0
	v_pk_mul_f32 v[4:5], v[94:95], v[94:95]
	s_nop 0
	v_add_f32_e32 v1, v5, v4
	s_nop 1
	v_mov_b32_dpp v4, v1 quad_perm:[1,0,3,2] row_mask:0xf bank_mask:0xf
	s_waitcnt lgkmcnt(0)
	v_add_f32_e32 v1, v1, v4
	s_nop 1
	v_mov_b32_dpp v4, v1 quad_perm:[2,3,0,1] row_mask:0xf bank_mask:0xf
	s_waitcnt lgkmcnt(0)
	v_add_f32_e32 v1, v1, v4
	s_nop 1
	v_mov_b32_dpp v4, v1 row_half_mirror row_mask:0xf bank_mask:0xf
	s_waitcnt lgkmcnt(0)
	v_add_f32_e32 v1, v1, v4
	s_nop 1
	v_mov_b32_dpp v4, v1 row_mirror row_mask:0xf bank_mask:0xf
	s_and_saveexec_b64 s[4:5], s[40:41]
	s_cbranch_execz .LBB0_558
	s_waitcnt lgkmcnt(0)
	v_add_f32_e32 v1, v1, v4
	ds_write_b32 v109, v1 offset:196
.LBB0_558:
	s_or_b64 exec, exec, s[4:5]
	v_mul_f32_e32 v1, 0xbfb8aa3b, v6
	v_exp_f32_e32 v1, v1
	v_mul_f32_e32 v2, 0xbfb8aa3b, v2
	v_exp_f32_e32 v2, v2
	v_add_u32_e32 v0, 0x210, v0
	v_add3_u32 v0, v83, v0, v78
	v_add_f32_e32 v1, 1.0, v1
	v_rcp_f32_e32 v5, v1
	ds_read_u16 v1, v0
	ds_read_u16 v6, v0 offset:32
	v_add_f32_e32 v2, 1.0, v2
	s_waitcnt lgkmcnt(2)
	v_rcp_f32_e32 v4, v2
	s_waitcnt lgkmcnt(1)
	v_lshlrev_b32_e32 v9, 16, v1
	s_waitcnt lgkmcnt(0)
	v_lshlrev_b32_e32 v8, 16, v6
	v_pk_mul_f32 v[72:73], v[4:5], v[8:9]
	s_nop 0
	v_pk_mul_f32 v[4:5], v[72:73], v[72:73]
	s_nop 0
	v_add_f32_e32 v1, v5, v4
	s_nop 1
	v_mov_b32_dpp v2, v1 quad_perm:[1,0,3,2] row_mask:0xf bank_mask:0xf
	s_waitcnt lgkmcnt(0)
	v_add_f32_e32 v1, v1, v2
	s_nop 1
	v_mov_b32_dpp v2, v1 quad_perm:[2,3,0,1] row_mask:0xf bank_mask:0xf
	s_waitcnt lgkmcnt(0)
	v_add_f32_e32 v1, v1, v2
	s_nop 1
	v_mov_b32_dpp v2, v1 row_half_mirror row_mask:0xf bank_mask:0xf
	s_waitcnt lgkmcnt(0)
	v_add_f32_e32 v1, v1, v2
	s_nop 1
	v_mov_b32_dpp v2, v1 row_mirror row_mask:0xf bank_mask:0xf
	s_and_saveexec_b64 s[4:5], s[40:41]
	s_cbranch_execz .LBB0_560
	s_waitcnt lgkmcnt(0)
	v_add_f32_e32 v1, v1, v2
	ds_write_b32 v109, v1 offset:200
.LBB0_560:
	s_or_b64 exec, exec, s[4:5]
	v_mul_f32_e32 v1, 0xbfb8aa3b, v7
	s_waitcnt lgkmcnt(0)
	v_mul_f32_e32 v2, 0xbfb8aa3b, v3
	v_exp_f32_e32 v1, v1
	v_exp_f32_e32 v2, v2
	ds_read_u16 v3, v0 offset:528
	ds_read_u16 v4, v0 offset:560
	v_add_f32_e32 v1, 1.0, v1
	v_add_f32_e32 v0, 1.0, v2
	v_rcp_f32_e32 v1, v1
	v_rcp_f32_e32 v0, v0
	s_waitcnt lgkmcnt(1)
	v_lshlrev_b32_e32 v3, 16, v3
	s_waitcnt lgkmcnt(0)
	v_lshlrev_b32_e32 v2, 16, v4
	v_pk_mul_f32 v[68:69], v[0:1], v[2:3]
	s_nop 0
	v_pk_mul_f32 v[0:1], v[68:69], v[68:69]
	s_nop 0
	v_add_f32_e32 v0, v1, v0
	s_nop 1
	v_mov_b32_dpp v1, v0 quad_perm:[1,0,3,2] row_mask:0xf bank_mask:0xf
	s_waitcnt lgkmcnt(0)
	v_add_f32_e32 v0, v0, v1
	s_nop 1
	v_mov_b32_dpp v1, v0 quad_perm:[2,3,0,1] row_mask:0xf bank_mask:0xf
	s_waitcnt lgkmcnt(0)
	v_add_f32_e32 v0, v0, v1
	s_nop 1
	v_mov_b32_dpp v1, v0 row_half_mirror row_mask:0xf bank_mask:0xf
	s_waitcnt lgkmcnt(0)
	v_add_f32_e32 v0, v0, v1
	s_nop 1
	v_mov_b32_dpp v1, v0 row_mirror row_mask:0xf bank_mask:0xf
	s_and_saveexec_b64 s[4:5], s[40:41]
	s_cbranch_execz .LBB0_562
	s_waitcnt lgkmcnt(0)
	v_add_f32_e32 v0, v0, v1
	ds_write_b32 v109, v0 offset:204
